# E44: block MFMA order 'snake': m outer, (bj,n) accumulators visited boustrophedon so neighbouring accumulators always share the A or the B fragment, k inner; rest as E30
# speedup vs baseline: 1.0183x; 1.0047x over previous
.Lcm1_skip:
.LBB0_225:
	ds_read_b128 v[128:131], v157
	ds_read_b128 v[132:135], v157 offset:1024
	ds_read_b128 v[146:149], v157 offset:2048
	ds_read_b128 v[164:167], v157 offset:3072
	ds_read_b128 v[168:171], v159
	ds_read_b128 v[172:175], v159 offset:1024
	ds_read_b128 v[176:179], v159 offset:2048
	ds_read_b128 v[180:183], v159 offset:3072
	s_add_u32 s36, s22, 0xfff80080
	s_addc_u32 s37, s23, -1
	s_cmp_eq_u32 s78, 28
	s_cselect_b32 s81, s5, s37
	s_cselect_b32 s80, s14, s36
	s_cselect_b32 vcc_hi, s20, s45
	s_cselect_b32 vcc_lo, s21, s24
	s_add_i32 m0, s77, 0xc000
	ds_read_b128 v[184:187], v161
	ds_read_b128 v[188:191], v161 offset:1024
	ds_read_b128 v[192:195], v161 offset:2048
	ds_read_b128 v[196:199], v161 offset:3072
	ds_read_b128 v[200:203], v161 offset:4096
	ds_read_b128 v[204:207], v161 offset:5120
	ds_read_b128 v[208:211], v161 offset:6144
	ds_read_b128 v[212:215], v161 offset:7168
	global_load_lds_dwordx4 v140, s[22:23]
	s_add_i32 m0, s77, 0xe000
	s_nop 0
	s_add_u32 s98, s22, s6
	s_addc_u32 s99, s23, s7
	global_load_lds_dwordx4 v140, s[98:99]
	s_waitcnt vmcnt(8)
	s_waitcnt lgkmcnt(0)
	s_barrier
	s_setprio 1
	s_waitcnt lgkmcnt(0)
	v_mfma_i32_16x16x64_i8 v[0:3], v[128:131], v[184:187], v[0:3]
	v_mfma_i32_16x16x64_i8 v[0:3], v[132:135], v[188:191], v[0:3]
	v_mfma_i32_16x16x64_i8 v[56:59], v[146:149], v[184:187], v[56:59]
	v_mfma_i32_16x16x64_i8 v[56:59], v[164:167], v[188:191], v[56:59]
	v_mfma_i32_16x16x64_i8 v[88:91], v[168:171], v[184:187], v[88:91]
	v_mfma_i32_16x16x64_i8 v[88:91], v[172:175], v[188:191], v[88:91]
	v_mfma_i32_16x16x64_i8 v[120:123], v[176:179], v[184:187], v[120:123]
	v_mfma_i32_16x16x64_i8 v[120:123], v[180:183], v[188:191], v[120:123]
	v_mfma_i32_16x16x64_i8 v[116:119], v[176:179], v[192:195], v[116:119]
	v_mfma_i32_16x16x64_i8 v[116:119], v[180:183], v[196:199], v[116:119]
	v_mfma_i32_16x16x64_i8 v[84:87], v[168:171], v[192:195], v[84:87]
	v_mfma_i32_16x16x64_i8 v[84:87], v[172:175], v[196:199], v[84:87]
	v_mfma_i32_16x16x64_i8 v[52:55], v[146:149], v[192:195], v[52:55]
	v_mfma_i32_16x16x64_i8 v[52:55], v[164:167], v[196:199], v[52:55]
	v_mfma_i32_16x16x64_i8 v[4:7], v[128:131], v[192:195], v[4:7]
	v_mfma_i32_16x16x64_i8 v[4:7], v[132:135], v[196:199], v[4:7]
	s_setprio 0
	s_setprio 1
	v_mfma_i32_16x16x64_i8 v[12:15], v[128:131], v[200:203], v[12:15]
	v_mfma_i32_16x16x64_i8 v[12:15], v[132:135], v[204:207], v[12:15]
	v_mfma_i32_16x16x64_i8 v[48:51], v[146:149], v[200:203], v[48:51]
	v_mfma_i32_16x16x64_i8 v[48:51], v[164:167], v[204:207], v[48:51]
	v_mfma_i32_16x16x64_i8 v[80:83], v[168:171], v[200:203], v[80:83]
	v_mfma_i32_16x16x64_i8 v[80:83], v[172:175], v[204:207], v[80:83]
	v_mfma_i32_16x16x64_i8 v[112:115], v[176:179], v[200:203], v[112:115]
	v_mfma_i32_16x16x64_i8 v[112:115], v[180:183], v[204:207], v[112:115]
	v_mfma_i32_16x16x64_i8 v[108:111], v[176:179], v[208:211], v[108:111]
	v_mfma_i32_16x16x64_i8 v[108:111], v[180:183], v[212:215], v[108:111]
	v_mfma_i32_16x16x64_i8 v[76:79], v[168:171], v[208:211], v[76:79]
	v_mfma_i32_16x16x64_i8 v[76:79], v[172:175], v[212:215], v[76:79]
	s_setprio 2
	s_barrier
	v_mfma_i32_16x16x64_i8 v[44:47], v[146:149], v[208:211], v[44:47]
	v_mfma_i32_16x16x64_i8 v[44:47], v[164:167], v[212:215], v[44:47]
	v_mfma_i32_16x16x64_i8 v[8:11], v[128:131], v[208:211], v[8:11]
	v_mfma_i32_16x16x64_i8 v[8:11], v[132:135], v[212:215], v[8:11]
	s_setprio 0
	s_add_i32 s36, s86, s63
	s_mov_b32 m0, s36
	ds_read_b128 v[184:187], v161 offset:16384
	ds_read_b128 v[188:191], v161 offset:17408
	ds_read_b128 v[192:195], v161 offset:18432
	ds_read_b128 v[196:199], v161 offset:19456
	ds_read_b128 v[200:203], v161 offset:20480
	ds_read_b128 v[204:207], v161 offset:21504
	ds_read_b128 v[208:211], v161 offset:22528
	ds_read_b128 v[212:215], v161 offset:23552
	global_load_lds_dwordx4 v138, vcc
	s_add_i32 m0, s36, 0x2000
	s_add_i32 s36, s87, s63
	s_add_u32 s98, vcc_lo, s6
	s_addc_u32 s99, vcc_hi, s7
	global_load_lds_dwordx4 v138, s[98:99]
	s_mov_b32 m0, s36
	s_nop 0
	s_add_u32 s98, vcc_lo, s8
	s_addc_u32 s99, vcc_hi, s9
	global_load_lds_dwordx4 v138, s[98:99]
	s_add_i32 m0, s36, 0x2000
	s_nop 0
	s_add_u32 s98, vcc_lo, s10
	s_addc_u32 s99, vcc_hi, s11
	global_load_lds_dwordx4 v138, s[98:99]
	s_mov_b32 m0, s77
	s_nop 0
	global_load_lds_dwordx4 v136, s[80:81]
	s_mov_b32 m0, s97
	s_nop 0
	s_add_u32 s98, s80, s6
	s_addc_u32 s99, s81, s7
	global_load_lds_dwordx4 v136, s[98:99]
	s_waitcnt vmcnt(8)
	s_waitcnt lgkmcnt(0)
	s_barrier
	s_setprio 1
	s_waitcnt lgkmcnt(0)
	v_mfma_i32_16x16x64_i8 v[20:23], v[128:131], v[184:187], v[20:23]
	v_mfma_i32_16x16x64_i8 v[20:23], v[132:135], v[188:191], v[20:23]
	v_mfma_i32_16x16x64_i8 v[40:43], v[146:149], v[184:187], v[40:43]
	v_mfma_i32_16x16x64_i8 v[40:43], v[164:167], v[188:191], v[40:43]
	v_mfma_i32_16x16x64_i8 v[72:75], v[168:171], v[184:187], v[72:75]
	v_mfma_i32_16x16x64_i8 v[72:75], v[172:175], v[188:191], v[72:75]
	v_mfma_i32_16x16x64_i8 v[104:107], v[176:179], v[184:187], v[104:107]
	v_mfma_i32_16x16x64_i8 v[104:107], v[180:183], v[188:191], v[104:107]
	v_mfma_i32_16x16x64_i8 v[100:103], v[176:179], v[192:195], v[100:103]
	v_mfma_i32_16x16x64_i8 v[100:103], v[180:183], v[196:199], v[100:103]
	v_mfma_i32_16x16x64_i8 v[68:71], v[168:171], v[192:195], v[68:71]
	v_mfma_i32_16x16x64_i8 v[68:71], v[172:175], v[196:199], v[68:71]
	v_mfma_i32_16x16x64_i8 v[36:39], v[146:149], v[192:195], v[36:39]
	v_mfma_i32_16x16x64_i8 v[36:39], v[164:167], v[196:199], v[36:39]
	v_mfma_i32_16x16x64_i8 v[16:19], v[128:131], v[192:195], v[16:19]
	v_mfma_i32_16x16x64_i8 v[16:19], v[132:135], v[196:199], v[16:19]
	s_setprio 0
	s_setprio 1
	v_mfma_i32_16x16x64_i8 v[24:27], v[128:131], v[200:203], v[24:27]
	v_mfma_i32_16x16x64_i8 v[24:27], v[132:135], v[204:207], v[24:27]
	v_mfma_i32_16x16x64_i8 v[32:35], v[146:149], v[200:203], v[32:35]
	v_mfma_i32_16x16x64_i8 v[32:35], v[164:167], v[204:207], v[32:35]
	v_mfma_i32_16x16x64_i8 v[64:67], v[168:171], v[200:203], v[64:67]
	v_mfma_i32_16x16x64_i8 v[64:67], v[172:175], v[204:207], v[64:67]
	v_mfma_i32_16x16x64_i8 v[96:99], v[176:179], v[200:203], v[96:99]
	v_mfma_i32_16x16x64_i8 v[96:99], v[180:183], v[204:207], v[96:99]
	v_mfma_i32_16x16x64_i8 v[124:127], v[176:179], v[208:211], v[124:127]
	v_mfma_i32_16x16x64_i8 v[124:127], v[180:183], v[212:215], v[124:127]
	v_mfma_i32_16x16x64_i8 v[92:95], v[168:171], v[208:211], v[92:95]
	v_mfma_i32_16x16x64_i8 v[92:95], v[172:175], v[212:215], v[92:95]
	s_setprio 2
	s_barrier
	v_mfma_i32_16x16x64_i8 v[60:63], v[146:149], v[208:211], v[60:63]
	v_mfma_i32_16x16x64_i8 v[60:63], v[164:167], v[212:215], v[60:63]
	v_mfma_i32_16x16x64_i8 v[28:31], v[128:131], v[208:211], v[28:31]
	v_mfma_i32_16x16x64_i8 v[28:31], v[132:135], v[212:215], v[28:31]
	s_setprio 0
	s_add_i32 s36, 0, 0x18000
	v_add_u32_e32 v152, s36, v153
	s_add_i32 s37, 0, 0x1c000
	ds_read_b128 v[128:131], v152
	ds_read_b128 v[132:135], v152 offset:1024
	ds_read_b128 v[146:149], v152 offset:2048
	ds_read_b128 v[164:167], v152 offset:3072
	v_add_u32_e32 v152, s37, v153
	ds_read_b128 v[168:171], v152
	ds_read_b128 v[172:175], v152 offset:1024
	ds_read_b128 v[176:179], v152 offset:2048
	ds_read_b128 v[180:183], v152 offset:3072
	s_mov_b32 m0, s33
	ds_read_b128 v[184:187], v161 offset:32768
	ds_read_b128 v[188:191], v161 offset:33792
	ds_read_b128 v[192:195], v161 offset:34816
	ds_read_b128 v[196:199], v161 offset:35840
	ds_read_b128 v[200:203], v161 offset:36864
	ds_read_b128 v[204:207], v161 offset:37888
	ds_read_b128 v[208:211], v161 offset:38912
	ds_read_b128 v[212:215], v161 offset:39936
	s_add_u32 s98, s80, s8
	s_addc_u32 s99, s81, s9
	global_load_lds_dwordx4 v136, s[98:99]
	s_mov_b32 m0, s93
	s_nop 0
	s_add_u32 s98, s80, s10
	s_addc_u32 s99, s81, s11
	global_load_lds_dwordx4 v136, s[98:99]
	s_waitcnt vmcnt(8)
	s_waitcnt lgkmcnt(0)
	s_barrier
	s_setprio 1
	s_waitcnt lgkmcnt(0)
	v_mfma_i32_16x16x64_i8 v[0:3], v[128:131], v[184:187], v[0:3]
	v_mfma_i32_16x16x64_i8 v[0:3], v[132:135], v[188:191], v[0:3]
	v_mfma_i32_16x16x64_i8 v[56:59], v[146:149], v[184:187], v[56:59]
	v_mfma_i32_16x16x64_i8 v[56:59], v[164:167], v[188:191], v[56:59]
	v_mfma_i32_16x16x64_i8 v[88:91], v[168:171], v[184:187], v[88:91]
	v_mfma_i32_16x16x64_i8 v[88:91], v[172:175], v[188:191], v[88:91]
	v_mfma_i32_16x16x64_i8 v[120:123], v[176:179], v[184:187], v[120:123]
	v_mfma_i32_16x16x64_i8 v[120:123], v[180:183], v[188:191], v[120:123]
	v_mfma_i32_16x16x64_i8 v[116:119], v[176:179], v[192:195], v[116:119]
	v_mfma_i32_16x16x64_i8 v[116:119], v[180:183], v[196:199], v[116:119]
	v_mfma_i32_16x16x64_i8 v[84:87], v[168:171], v[192:195], v[84:87]
	v_mfma_i32_16x16x64_i8 v[84:87], v[172:175], v[196:199], v[84:87]
	v_mfma_i32_16x16x64_i8 v[52:55], v[146:149], v[192:195], v[52:55]
	v_mfma_i32_16x16x64_i8 v[52:55], v[164:167], v[196:199], v[52:55]
	v_mfma_i32_16x16x64_i8 v[4:7], v[128:131], v[192:195], v[4:7]
	v_mfma_i32_16x16x64_i8 v[4:7], v[132:135], v[196:199], v[4:7]
	s_setprio 0
	s_setprio 1
	v_mfma_i32_16x16x64_i8 v[12:15], v[128:131], v[200:203], v[12:15]
	v_mfma_i32_16x16x64_i8 v[12:15], v[132:135], v[204:207], v[12:15]
	v_mfma_i32_16x16x64_i8 v[48:51], v[146:149], v[200:203], v[48:51]
	v_mfma_i32_16x16x64_i8 v[48:51], v[164:167], v[204:207], v[48:51]
	v_mfma_i32_16x16x64_i8 v[80:83], v[168:171], v[200:203], v[80:83]
	v_mfma_i32_16x16x64_i8 v[80:83], v[172:175], v[204:207], v[80:83]
	v_mfma_i32_16x16x64_i8 v[112:115], v[176:179], v[200:203], v[112:115]
	v_mfma_i32_16x16x64_i8 v[112:115], v[180:183], v[204:207], v[112:115]
	v_mfma_i32_16x16x64_i8 v[108:111], v[176:179], v[208:211], v[108:111]
	v_mfma_i32_16x16x64_i8 v[108:111], v[180:183], v[212:215], v[108:111]
	v_mfma_i32_16x16x64_i8 v[76:79], v[168:171], v[208:211], v[76:79]
	v_mfma_i32_16x16x64_i8 v[76:79], v[172:175], v[212:215], v[76:79]
	s_setprio 2
	s_barrier
	v_mfma_i32_16x16x64_i8 v[44:47], v[146:149], v[208:211], v[44:47]
	v_mfma_i32_16x16x64_i8 v[44:47], v[164:167], v[212:215], v[44:47]
	v_mfma_i32_16x16x64_i8 v[8:11], v[128:131], v[208:211], v[8:11]
	v_mfma_i32_16x16x64_i8 v[8:11], v[132:135], v[212:215], v[8:11]
	s_setprio 0
	s_add_i32 s36, s36, s63
	s_mov_b32 m0, s36
	ds_read_b128 v[184:187], v161 offset:49152
	ds_read_b128 v[188:191], v161 offset:50176
	ds_read_b128 v[192:195], v161 offset:51200
	ds_read_b128 v[196:199], v161 offset:52224
	ds_read_b128 v[200:203], v161 offset:53248
	ds_read_b128 v[204:207], v161 offset:54272
	ds_read_b128 v[208:211], v161 offset:55296
	ds_read_b128 v[212:215], v161 offset:56320
	s_add_u32 s98, vcc_lo, s46
	s_addc_u32 s99, vcc_hi, s47
	global_load_lds_dwordx4 v138, s[98:99]
	s_add_i32 m0, s36, 0x2000
	s_add_i32 s36, s37, s63
	s_add_u32 s98, vcc_lo, s48
	s_addc_u32 s99, vcc_hi, s49
	global_load_lds_dwordx4 v138, s[98:99]
	s_mov_b32 m0, s36
	s_add_u32 s98, vcc_lo, s54
	s_addc_u32 s99, vcc_hi, s55
	global_load_lds_dwordx4 v138, s[98:99]
	s_add_i32 m0, s36, 0x2000
	s_nop 0
	s_add_u32 s98, vcc_lo, s56
	s_addc_u32 s99, vcc_hi, s57
	global_load_lds_dwordx4 v138, s[98:99]
	s_mov_b32 m0, s95
	s_nop 0
	s_add_u32 s98, s80, s46
	s_addc_u32 s99, s81, s47
	global_load_lds_dwordx4 v136, s[98:99]
	s_mov_b32 m0, s82
	s_nop 0
	s_add_u32 s98, s80, s48
	s_addc_u32 s99, s81, s49
	global_load_lds_dwordx4 v136, s[98:99]
	s_waitcnt vmcnt(8)
	s_waitcnt lgkmcnt(0)
	s_barrier
	s_setprio 1
	s_waitcnt lgkmcnt(0)
	v_mfma_i32_16x16x64_i8 v[20:23], v[128:131], v[184:187], v[20:23]
	v_mfma_i32_16x16x64_i8 v[20:23], v[132:135], v[188:191], v[20:23]
	v_mfma_i32_16x16x64_i8 v[40:43], v[146:149], v[184:187], v[40:43]
	v_mfma_i32_16x16x64_i8 v[40:43], v[164:167], v[188:191], v[40:43]
	v_mfma_i32_16x16x64_i8 v[72:75], v[168:171], v[184:187], v[72:75]
	v_mfma_i32_16x16x64_i8 v[72:75], v[172:175], v[188:191], v[72:75]
	v_mfma_i32_16x16x64_i8 v[104:107], v[176:179], v[184:187], v[104:107]
	v_mfma_i32_16x16x64_i8 v[104:107], v[180:183], v[188:191], v[104:107]
	v_mfma_i32_16x16x64_i8 v[100:103], v[176:179], v[192:195], v[100:103]
	v_mfma_i32_16x16x64_i8 v[100:103], v[180:183], v[196:199], v[100:103]
	v_mfma_i32_16x16x64_i8 v[68:71], v[168:171], v[192:195], v[68:71]
	v_mfma_i32_16x16x64_i8 v[68:71], v[172:175], v[196:199], v[68:71]
	v_mfma_i32_16x16x64_i8 v[36:39], v[146:149], v[192:195], v[36:39]
	v_mfma_i32_16x16x64_i8 v[36:39], v[164:167], v[196:199], v[36:39]
	v_mfma_i32_16x16x64_i8 v[16:19], v[128:131], v[192:195], v[16:19]
	v_mfma_i32_16x16x64_i8 v[16:19], v[132:135], v[196:199], v[16:19]
	s_setprio 0
	s_setprio 1
	v_mfma_i32_16x16x64_i8 v[24:27], v[128:131], v[200:203], v[24:27]
	v_mfma_i32_16x16x64_i8 v[24:27], v[132:135], v[204:207], v[24:27]
	v_mfma_i32_16x16x64_i8 v[32:35], v[146:149], v[200:203], v[32:35]
	v_mfma_i32_16x16x64_i8 v[32:35], v[164:167], v[204:207], v[32:35]
	v_mfma_i32_16x16x64_i8 v[64:67], v[168:171], v[200:203], v[64:67]
	v_mfma_i32_16x16x64_i8 v[64:67], v[172:175], v[204:207], v[64:67]
	v_mfma_i32_16x16x64_i8 v[96:99], v[176:179], v[200:203], v[96:99]
	v_mfma_i32_16x16x64_i8 v[96:99], v[180:183], v[204:207], v[96:99]
	v_mfma_i32_16x16x64_i8 v[124:127], v[176:179], v[208:211], v[124:127]
	v_mfma_i32_16x16x64_i8 v[124:127], v[180:183], v[212:215], v[124:127]
	v_mfma_i32_16x16x64_i8 v[92:95], v[168:171], v[208:211], v[92:95]
	v_mfma_i32_16x16x64_i8 v[92:95], v[172:175], v[212:215], v[92:95]
	s_setprio 2
	s_barrier
	v_mfma_i32_16x16x64_i8 v[60:63], v[146:149], v[208:211], v[60:63]
	v_mfma_i32_16x16x64_i8 v[60:63], v[164:167], v[212:215], v[60:63]
	v_mfma_i32_16x16x64_i8 v[28:31], v[128:131], v[208:211], v[28:31]
	v_mfma_i32_16x16x64_i8 v[28:31], v[132:135], v[212:215], v[28:31]
	s_setprio 0
	s_add_i32 s78, s78, 2
	s_add_u32 s24, s24, 0x100
	s_addc_u32 s45, s45, 0
	s_add_u32 s22, s22, 0x100
	s_addc_u32 s23, s23, 0
	s_cmp_gt_u32 s78, 29
	s_cbranch_scc0 .LBB0_225
	v_readlane_b32 s14, v250, 9
	v_readlane_b32 s15, v250, 10
	s_and_b64 vcc, exec, s[14:15]
	s_cbranch_vccz .LBB0_228
	s_barrier

.LBB0_298:
	ds_read_b128 v[128:131], v153
	ds_read_b128 v[132:135], v153 offset:1024
	ds_read_b128 v[146:149], v153 offset:2048
	ds_read_b128 v[158:161], v153 offset:3072
	ds_read_b128 v[162:165], v154
	ds_read_b128 v[166:169], v154 offset:1024
	ds_read_b128 v[170:173], v154 offset:2048
	ds_read_b128 v[174:177], v154 offset:3072
	s_add_u32 s36, s78, 0xfff00080
	s_addc_u32 s37, s79, -1
	s_cmp_eq_u32 s81, 60
	s_cselect_b32 s97, s5, s37
	s_cselect_b32 s96, s14, s36
	s_cselect_b32 vcc_hi, s20, s80
	s_cselect_b32 vcc_lo, s21, s22
	s_add_i32 m0, s33, 0xc000
	ds_read_b128 v[178:181], v155
	ds_read_b128 v[182:185], v155 offset:1024
	ds_read_b128 v[186:189], v155 offset:2048
	ds_read_b128 v[190:193], v155 offset:3072
	ds_read_b128 v[194:197], v155 offset:4096
	ds_read_b128 v[198:201], v155 offset:5120
	ds_read_b128 v[202:205], v155 offset:6144
	ds_read_b128 v[206:209], v155 offset:7168
	global_load_lds_dwordx4 v140, s[78:79]
	s_add_i32 m0, s33, 0xe000
	s_nop 0
	s_add_u32 s98, s78, s0
	s_addc_u32 s99, s79, s1
	global_load_lds_dwordx4 v140, s[98:99]
	s_waitcnt vmcnt(8)
	s_waitcnt lgkmcnt(0)
	s_barrier
	s_setprio 1
	s_waitcnt lgkmcnt(0)
	v_mfma_f32_16x16x32_bf16 v[124:127], v[128:131], v[178:181], v[124:127]
	v_mfma_f32_16x16x32_bf16 v[124:127], v[132:135], v[182:185], v[124:127]
	v_mfma_f32_16x16x32_bf16 v[120:123], v[146:149], v[178:181], v[120:123]
	v_mfma_f32_16x16x32_bf16 v[120:123], v[158:161], v[182:185], v[120:123]
	v_mfma_f32_16x16x32_bf16 v[116:119], v[162:165], v[178:181], v[116:119]
	v_mfma_f32_16x16x32_bf16 v[116:119], v[166:169], v[182:185], v[116:119]
	v_mfma_f32_16x16x32_bf16 v[104:107], v[170:173], v[178:181], v[104:107]
	v_mfma_f32_16x16x32_bf16 v[104:107], v[174:177], v[182:185], v[104:107]
	v_mfma_f32_16x16x32_bf16 v[88:91], v[170:173], v[186:189], v[88:91]
	v_mfma_f32_16x16x32_bf16 v[88:91], v[174:177], v[190:193], v[88:91]
	v_mfma_f32_16x16x32_bf16 v[96:99], v[162:165], v[186:189], v[96:99]
	v_mfma_f32_16x16x32_bf16 v[96:99], v[166:169], v[190:193], v[96:99]
	v_mfma_f32_16x16x32_bf16 v[108:111], v[146:149], v[186:189], v[108:111]
	v_mfma_f32_16x16x32_bf16 v[108:111], v[158:161], v[190:193], v[108:111]
	v_mfma_f32_16x16x32_bf16 v[112:115], v[128:131], v[186:189], v[112:115]
	v_mfma_f32_16x16x32_bf16 v[112:115], v[132:135], v[190:193], v[112:115]
	s_setprio 0
	s_setprio 1
	v_mfma_f32_16x16x32_bf16 v[100:103], v[128:131], v[194:197], v[100:103]
	v_mfma_f32_16x16x32_bf16 v[100:103], v[132:135], v[198:201], v[100:103]
	v_mfma_f32_16x16x32_bf16 v[92:95], v[146:149], v[194:197], v[92:95]
	v_mfma_f32_16x16x32_bf16 v[92:95], v[158:161], v[198:201], v[92:95]
	v_mfma_f32_16x16x32_bf16 v[80:83], v[162:165], v[194:197], v[80:83]
	v_mfma_f32_16x16x32_bf16 v[80:83], v[166:169], v[198:201], v[80:83]
	v_mfma_f32_16x16x32_bf16 v[72:75], v[170:173], v[194:197], v[72:75]
	v_mfma_f32_16x16x32_bf16 v[72:75], v[174:177], v[198:201], v[72:75]
	v_mfma_f32_16x16x32_bf16 v[64:67], v[170:173], v[202:205], v[64:67]
	v_mfma_f32_16x16x32_bf16 v[64:67], v[174:177], v[206:209], v[64:67]
	v_mfma_f32_16x16x32_bf16 v[68:71], v[162:165], v[202:205], v[68:71]
	v_mfma_f32_16x16x32_bf16 v[68:71], v[166:169], v[206:209], v[68:71]
	s_setprio 2
	s_barrier
	v_mfma_f32_16x16x32_bf16 v[76:79], v[146:149], v[202:205], v[76:79]
	v_mfma_f32_16x16x32_bf16 v[76:79], v[158:161], v[206:209], v[76:79]
	v_mfma_f32_16x16x32_bf16 v[84:87], v[128:131], v[202:205], v[84:87]
	v_mfma_f32_16x16x32_bf16 v[84:87], v[132:135], v[206:209], v[84:87]
	s_setprio 0
	s_add_i32 s36, s82, s63
	s_mov_b32 m0, s36
	ds_read_b128 v[178:181], v155 offset:16384
	ds_read_b128 v[182:185], v155 offset:17408
	ds_read_b128 v[186:189], v155 offset:18432
	ds_read_b128 v[190:193], v155 offset:19456
	ds_read_b128 v[194:197], v155 offset:20480
	ds_read_b128 v[198:201], v155 offset:21504
	ds_read_b128 v[202:205], v155 offset:22528
	ds_read_b128 v[206:209], v155 offset:23552
	global_load_lds_dwordx4 v138, vcc
	s_add_i32 m0, s36, 0x2000
	s_add_i32 s36, s83, s63
	s_add_u32 s98, vcc_lo, s0
	s_addc_u32 s99, vcc_hi, s1
	global_load_lds_dwordx4 v138, s[98:99]
	s_mov_b32 m0, s36
	s_nop 0
	s_add_u32 s98, vcc_lo, s6
	s_addc_u32 s99, vcc_hi, s7
	global_load_lds_dwordx4 v138, s[98:99]
	s_add_i32 m0, s36, 0x2000
	s_nop 0
	s_add_u32 s98, vcc_lo, s8
	s_addc_u32 s99, vcc_hi, s9
	global_load_lds_dwordx4 v138, s[98:99]
	s_mov_b32 m0, s33
	s_nop 0
	global_load_lds_dwordx4 v136, s[96:97]
	s_mov_b32 m0, s55
	s_nop 0
	s_add_u32 s98, s96, s0
	s_addc_u32 s99, s97, s1
	global_load_lds_dwordx4 v136, s[98:99]
	s_waitcnt vmcnt(8)
	s_waitcnt lgkmcnt(0)
	s_barrier
	s_setprio 1
	s_waitcnt lgkmcnt(0)
	v_mfma_f32_16x16x32_bf16 v[60:63], v[128:131], v[178:181], v[60:63]
	v_mfma_f32_16x16x32_bf16 v[60:63], v[132:135], v[182:185], v[60:63]
	v_mfma_f32_16x16x32_bf16 v[56:59], v[146:149], v[178:181], v[56:59]
	v_mfma_f32_16x16x32_bf16 v[56:59], v[158:161], v[182:185], v[56:59]
	v_mfma_f32_16x16x32_bf16 v[48:51], v[162:165], v[178:181], v[48:51]
	v_mfma_f32_16x16x32_bf16 v[48:51], v[166:169], v[182:185], v[48:51]
	v_mfma_f32_16x16x32_bf16 v[40:43], v[170:173], v[178:181], v[40:43]
	v_mfma_f32_16x16x32_bf16 v[40:43], v[174:177], v[182:185], v[40:43]
	v_mfma_f32_16x16x32_bf16 v[24:27], v[170:173], v[186:189], v[24:27]
	v_mfma_f32_16x16x32_bf16 v[24:27], v[174:177], v[190:193], v[24:27]
	v_mfma_f32_16x16x32_bf16 v[32:35], v[162:165], v[186:189], v[32:35]
	v_mfma_f32_16x16x32_bf16 v[32:35], v[166:169], v[190:193], v[32:35]
	v_mfma_f32_16x16x32_bf16 v[44:47], v[146:149], v[186:189], v[44:47]
	v_mfma_f32_16x16x32_bf16 v[44:47], v[158:161], v[190:193], v[44:47]
	v_mfma_f32_16x16x32_bf16 v[52:55], v[128:131], v[186:189], v[52:55]
	v_mfma_f32_16x16x32_bf16 v[52:55], v[132:135], v[190:193], v[52:55]
	s_setprio 0
	s_setprio 1
	v_mfma_f32_16x16x32_bf16 v[36:39], v[128:131], v[194:197], v[36:39]
	v_mfma_f32_16x16x32_bf16 v[36:39], v[132:135], v[198:201], v[36:39]
	v_mfma_f32_16x16x32_bf16 v[28:31], v[146:149], v[194:197], v[28:31]
	v_mfma_f32_16x16x32_bf16 v[28:31], v[158:161], v[198:201], v[28:31]
	v_mfma_f32_16x16x32_bf16 v[16:19], v[162:165], v[194:197], v[16:19]
	v_mfma_f32_16x16x32_bf16 v[16:19], v[166:169], v[198:201], v[16:19]
	v_mfma_f32_16x16x32_bf16 v[8:11], v[170:173], v[194:197], v[8:11]
	v_mfma_f32_16x16x32_bf16 v[8:11], v[174:177], v[198:201], v[8:11]
	v_mfma_f32_16x16x32_bf16 v[0:3], v[170:173], v[202:205], v[0:3]
	v_mfma_f32_16x16x32_bf16 v[0:3], v[174:177], v[206:209], v[0:3]
	v_mfma_f32_16x16x32_bf16 v[4:7], v[162:165], v[202:205], v[4:7]
	v_mfma_f32_16x16x32_bf16 v[4:7], v[166:169], v[206:209], v[4:7]
	s_setprio 2
	s_barrier
	v_mfma_f32_16x16x32_bf16 v[12:15], v[146:149], v[202:205], v[12:15]
	v_mfma_f32_16x16x32_bf16 v[12:15], v[158:161], v[206:209], v[12:15]
	v_mfma_f32_16x16x32_bf16 v[20:23], v[128:131], v[202:205], v[20:23]
	v_mfma_f32_16x16x32_bf16 v[20:23], v[132:135], v[206:209], v[20:23]
	s_setprio 0
	s_add_i32 s36, 0, 0x18000
	v_add_u32_e32 v157, s36, v152
	s_add_i32 s37, 0, 0x1c000
	ds_read_b128 v[128:131], v157
	ds_read_b128 v[132:135], v157 offset:1024
	ds_read_b128 v[146:149], v157 offset:2048
	ds_read_b128 v[158:161], v157 offset:3072
	v_add_u32_e32 v157, s37, v152
	ds_read_b128 v[162:165], v157
	ds_read_b128 v[166:169], v157 offset:1024
	ds_read_b128 v[170:173], v157 offset:2048
	ds_read_b128 v[174:177], v157 offset:3072
	s_mov_b32 m0, s57
	ds_read_b128 v[178:181], v155 offset:32768
	ds_read_b128 v[182:185], v155 offset:33792
	ds_read_b128 v[186:189], v155 offset:34816
	ds_read_b128 v[190:193], v155 offset:35840
	ds_read_b128 v[194:197], v155 offset:36864
	ds_read_b128 v[198:201], v155 offset:37888
	ds_read_b128 v[202:205], v155 offset:38912
	ds_read_b128 v[206:209], v155 offset:39936
	s_add_u32 s98, s96, s6
	s_addc_u32 s99, s97, s7
	global_load_lds_dwordx4 v136, s[98:99]
	s_mov_b32 m0, s59
	s_nop 0
	s_add_u32 s98, s96, s8
	s_addc_u32 s99, s97, s9
	global_load_lds_dwordx4 v136, s[98:99]
	s_waitcnt vmcnt(8)
	s_waitcnt lgkmcnt(0)
	s_barrier
	s_setprio 1
	s_waitcnt lgkmcnt(0)
	v_mfma_f32_16x16x32_bf16 v[124:127], v[128:131], v[178:181], v[124:127]
	v_mfma_f32_16x16x32_bf16 v[124:127], v[132:135], v[182:185], v[124:127]
	v_mfma_f32_16x16x32_bf16 v[120:123], v[146:149], v[178:181], v[120:123]
	v_mfma_f32_16x16x32_bf16 v[120:123], v[158:161], v[182:185], v[120:123]
	v_mfma_f32_16x16x32_bf16 v[116:119], v[162:165], v[178:181], v[116:119]
	v_mfma_f32_16x16x32_bf16 v[116:119], v[166:169], v[182:185], v[116:119]
	v_mfma_f32_16x16x32_bf16 v[104:107], v[170:173], v[178:181], v[104:107]
	v_mfma_f32_16x16x32_bf16 v[104:107], v[174:177], v[182:185], v[104:107]
	v_mfma_f32_16x16x32_bf16 v[88:91], v[170:173], v[186:189], v[88:91]
	v_mfma_f32_16x16x32_bf16 v[88:91], v[174:177], v[190:193], v[88:91]
	v_mfma_f32_16x16x32_bf16 v[96:99], v[162:165], v[186:189], v[96:99]
	v_mfma_f32_16x16x32_bf16 v[96:99], v[166:169], v[190:193], v[96:99]
	v_mfma_f32_16x16x32_bf16 v[108:111], v[146:149], v[186:189], v[108:111]
	v_mfma_f32_16x16x32_bf16 v[108:111], v[158:161], v[190:193], v[108:111]
	v_mfma_f32_16x16x32_bf16 v[112:115], v[128:131], v[186:189], v[112:115]
	v_mfma_f32_16x16x32_bf16 v[112:115], v[132:135], v[190:193], v[112:115]
	s_setprio 0
	s_setprio 1
	v_mfma_f32_16x16x32_bf16 v[100:103], v[128:131], v[194:197], v[100:103]
	v_mfma_f32_16x16x32_bf16 v[100:103], v[132:135], v[198:201], v[100:103]
	v_mfma_f32_16x16x32_bf16 v[92:95], v[146:149], v[194:197], v[92:95]
	v_mfma_f32_16x16x32_bf16 v[92:95], v[158:161], v[198:201], v[92:95]
	v_mfma_f32_16x16x32_bf16 v[80:83], v[162:165], v[194:197], v[80:83]
	v_mfma_f32_16x16x32_bf16 v[80:83], v[166:169], v[198:201], v[80:83]
	v_mfma_f32_16x16x32_bf16 v[72:75], v[170:173], v[194:197], v[72:75]
	v_mfma_f32_16x16x32_bf16 v[72:75], v[174:177], v[198:201], v[72:75]
	v_mfma_f32_16x16x32_bf16 v[64:67], v[170:173], v[202:205], v[64:67]
	v_mfma_f32_16x16x32_bf16 v[64:67], v[174:177], v[206:209], v[64:67]
	v_mfma_f32_16x16x32_bf16 v[68:71], v[162:165], v[202:205], v[68:71]
	v_mfma_f32_16x16x32_bf16 v[68:71], v[166:169], v[206:209], v[68:71]
	s_setprio 2
	s_barrier
	v_mfma_f32_16x16x32_bf16 v[76:79], v[146:149], v[202:205], v[76:79]
	v_mfma_f32_16x16x32_bf16 v[76:79], v[158:161], v[206:209], v[76:79]
	v_mfma_f32_16x16x32_bf16 v[84:87], v[128:131], v[202:205], v[84:87]
	v_mfma_f32_16x16x32_bf16 v[84:87], v[132:135], v[206:209], v[84:87]
	s_setprio 0
	s_add_i32 s36, s36, s63
	s_mov_b32 m0, s36
	ds_read_b128 v[178:181], v155 offset:49152
	ds_read_b128 v[182:185], v155 offset:50176
	ds_read_b128 v[186:189], v155 offset:51200
	ds_read_b128 v[190:193], v155 offset:52224
	ds_read_b128 v[194:197], v155 offset:53248
	ds_read_b128 v[198:201], v155 offset:54272
	ds_read_b128 v[202:205], v155 offset:55296
	ds_read_b128 v[206:209], v155 offset:56320
	s_add_u32 s98, vcc_lo, s24
	s_addc_u32 s99, vcc_hi, s25
	global_load_lds_dwordx4 v138, s[98:99]
	s_add_i32 m0, s36, 0x2000
	s_add_i32 s36, s37, s63
	s_add_u32 s98, vcc_lo, s34
	s_addc_u32 s99, vcc_hi, s35
	global_load_lds_dwordx4 v138, s[98:99]
	s_mov_b32 m0, s36
	s_add_u32 s98, vcc_lo, s12
	s_addc_u32 s99, vcc_hi, s13
	global_load_lds_dwordx4 v138, s[98:99]
	s_add_i32 m0, s36, 0x2000
	s_nop 0
	s_add_u32 s98, vcc_lo, s18
	s_addc_u32 s99, vcc_hi, s19
	global_load_lds_dwordx4 v138, s[98:99]
	s_mov_b32 m0, s68
	s_nop 0
	s_add_u32 s98, s96, s24
	s_addc_u32 s99, s97, s25
	global_load_lds_dwordx4 v136, s[98:99]
	s_mov_b32 m0, s69
	s_nop 0
	s_add_u32 s98, s96, s34
	s_addc_u32 s99, s97, s35
	global_load_lds_dwordx4 v136, s[98:99]
	s_waitcnt vmcnt(8)
	s_waitcnt lgkmcnt(0)
	s_barrier
	s_setprio 1
	s_waitcnt lgkmcnt(0)
	v_mfma_f32_16x16x32_bf16 v[60:63], v[128:131], v[178:181], v[60:63]
	v_mfma_f32_16x16x32_bf16 v[60:63], v[132:135], v[182:185], v[60:63]
	v_mfma_f32_16x16x32_bf16 v[56:59], v[146:149], v[178:181], v[56:59]
	v_mfma_f32_16x16x32_bf16 v[56:59], v[158:161], v[182:185], v[56:59]
	v_mfma_f32_16x16x32_bf16 v[48:51], v[162:165], v[178:181], v[48:51]
	v_mfma_f32_16x16x32_bf16 v[48:51], v[166:169], v[182:185], v[48:51]
	v_mfma_f32_16x16x32_bf16 v[40:43], v[170:173], v[178:181], v[40:43]
	v_mfma_f32_16x16x32_bf16 v[40:43], v[174:177], v[182:185], v[40:43]
	v_mfma_f32_16x16x32_bf16 v[24:27], v[170:173], v[186:189], v[24:27]
	v_mfma_f32_16x16x32_bf16 v[24:27], v[174:177], v[190:193], v[24:27]
	v_mfma_f32_16x16x32_bf16 v[32:35], v[162:165], v[186:189], v[32:35]
	v_mfma_f32_16x16x32_bf16 v[32:35], v[166:169], v[190:193], v[32:35]
	v_mfma_f32_16x16x32_bf16 v[44:47], v[146:149], v[186:189], v[44:47]
	v_mfma_f32_16x16x32_bf16 v[44:47], v[158:161], v[190:193], v[44:47]
	v_mfma_f32_16x16x32_bf16 v[52:55], v[128:131], v[186:189], v[52:55]
	v_mfma_f32_16x16x32_bf16 v[52:55], v[132:135], v[190:193], v[52:55]
	s_setprio 0
	s_setprio 1
	v_mfma_f32_16x16x32_bf16 v[36:39], v[128:131], v[194:197], v[36:39]
	v_mfma_f32_16x16x32_bf16 v[36:39], v[132:135], v[198:201], v[36:39]
	v_mfma_f32_16x16x32_bf16 v[28:31], v[146:149], v[194:197], v[28:31]
	v_mfma_f32_16x16x32_bf16 v[28:31], v[158:161], v[198:201], v[28:31]
	v_mfma_f32_16x16x32_bf16 v[16:19], v[162:165], v[194:197], v[16:19]
	v_mfma_f32_16x16x32_bf16 v[16:19], v[166:169], v[198:201], v[16:19]
	v_mfma_f32_16x16x32_bf16 v[8:11], v[170:173], v[194:197], v[8:11]
	v_mfma_f32_16x16x32_bf16 v[8:11], v[174:177], v[198:201], v[8:11]
	v_mfma_f32_16x16x32_bf16 v[0:3], v[170:173], v[202:205], v[0:3]
	v_mfma_f32_16x16x32_bf16 v[0:3], v[174:177], v[206:209], v[0:3]
	v_mfma_f32_16x16x32_bf16 v[4:7], v[162:165], v[202:205], v[4:7]
	v_mfma_f32_16x16x32_bf16 v[4:7], v[166:169], v[206:209], v[4:7]
	s_setprio 2
	s_barrier
	v_mfma_f32_16x16x32_bf16 v[12:15], v[146:149], v[202:205], v[12:15]
	v_mfma_f32_16x16x32_bf16 v[12:15], v[158:161], v[206:209], v[12:15]
	v_mfma_f32_16x16x32_bf16 v[20:23], v[128:131], v[202:205], v[20:23]
	v_mfma_f32_16x16x32_bf16 v[20:23], v[132:135], v[206:209], v[20:23]
	s_setprio 0
	s_add_i32 s81, s81, 2
	s_add_u32 s22, s22, 0x100
	s_addc_u32 s80, s80, 0
	s_add_u32 s78, s78, 0x100
	s_addc_u32 s79, s79, 0
	s_cmp_gt_u32 s81, 61
	s_cbranch_scc0 .LBB0_298
	s_and_b64 vcc, exec, s[26:27]
	s_cbranch_vccz .LBB0_301
	s_barrier

.LBB0_627:
	ds_read_b128 v[128:131], v151
	ds_read_b128 v[142:145], v151 offset:1024
	ds_read_b128 v[146:149], v151 offset:2048
	ds_read_b128 v[154:157], v151 offset:3072
	ds_read_b128 v[158:161], v152
	ds_read_b128 v[162:165], v152 offset:1024
	ds_read_b128 v[166:169], v152 offset:2048
	ds_read_b128 v[170:173], v152 offset:3072
	s_add_u32 s50, s60, 0xfff00080
	s_addc_u32 s51, s61, -1
	s_cmp_eq_u32 s62, 60
	s_cselect_b32 s77, s5, s51
	s_cselect_b32 s76, s49, s50
	s_cselect_b32 s79, s47, s75
	s_cselect_b32 s78, s59, s74
	s_add_i32 m0, s20, 0xc000
	ds_read_b128 v[174:177], v153
	ds_read_b128 v[178:181], v153 offset:1024
	ds_read_b128 v[182:185], v153 offset:2048
	ds_read_b128 v[186:189], v153 offset:3072
	ds_read_b128 v[190:193], v153 offset:4096
	ds_read_b128 v[194:197], v153 offset:5120
	ds_read_b128 v[198:201], v153 offset:6144
	ds_read_b128 v[202:205], v153 offset:7168
	global_load_lds_dwordx4 v136, s[60:61]
	s_add_i32 m0, s20, 0xe000
	s_nop 0
	s_add_u32 s98, s60, s6
	s_addc_u32 s99, s61, s7
	global_load_lds_dwordx4 v136, s[98:99]
	s_waitcnt vmcnt(8)
	s_waitcnt lgkmcnt(0)
	s_barrier
	s_setprio 1
	s_waitcnt lgkmcnt(0)
	v_mfma_f32_16x16x32_bf16 v[124:127], v[128:131], v[174:177], v[124:127]
	v_mfma_f32_16x16x32_bf16 v[124:127], v[142:145], v[178:181], v[124:127]
	v_mfma_f32_16x16x32_bf16 v[120:123], v[146:149], v[174:177], v[120:123]
	v_mfma_f32_16x16x32_bf16 v[120:123], v[154:157], v[178:181], v[120:123]
	v_mfma_f32_16x16x32_bf16 v[92:95], v[158:161], v[174:177], v[92:95]
	v_mfma_f32_16x16x32_bf16 v[92:95], v[162:165], v[178:181], v[92:95]
	v_mfma_f32_16x16x32_bf16 v[88:91], v[166:169], v[174:177], v[88:91]
	v_mfma_f32_16x16x32_bf16 v[88:91], v[170:173], v[178:181], v[88:91]
	v_mfma_f32_16x16x32_bf16 v[80:83], v[166:169], v[182:185], v[80:83]
	v_mfma_f32_16x16x32_bf16 v[80:83], v[170:173], v[186:189], v[80:83]
	v_mfma_f32_16x16x32_bf16 v[84:87], v[158:161], v[182:185], v[84:87]
	v_mfma_f32_16x16x32_bf16 v[84:87], v[162:165], v[186:189], v[84:87]
	v_mfma_f32_16x16x32_bf16 v[112:115], v[146:149], v[182:185], v[112:115]
	v_mfma_f32_16x16x32_bf16 v[112:115], v[154:157], v[186:189], v[112:115]
	v_mfma_f32_16x16x32_bf16 v[116:119], v[128:131], v[182:185], v[116:119]
	v_mfma_f32_16x16x32_bf16 v[116:119], v[142:145], v[186:189], v[116:119]
	s_setprio 0
	s_setprio 1
	v_mfma_f32_16x16x32_bf16 v[108:111], v[128:131], v[190:193], v[108:111]
	v_mfma_f32_16x16x32_bf16 v[108:111], v[142:145], v[194:197], v[108:111]
	v_mfma_f32_16x16x32_bf16 v[104:107], v[146:149], v[190:193], v[104:107]
	v_mfma_f32_16x16x32_bf16 v[104:107], v[154:157], v[194:197], v[104:107]
	v_mfma_f32_16x16x32_bf16 v[76:79], v[158:161], v[190:193], v[76:79]
	v_mfma_f32_16x16x32_bf16 v[76:79], v[162:165], v[194:197], v[76:79]
	v_mfma_f32_16x16x32_bf16 v[72:75], v[166:169], v[190:193], v[72:75]
	v_mfma_f32_16x16x32_bf16 v[72:75], v[170:173], v[194:197], v[72:75]
	v_mfma_f32_16x16x32_bf16 v[64:67], v[166:169], v[198:201], v[64:67]
	v_mfma_f32_16x16x32_bf16 v[64:67], v[170:173], v[202:205], v[64:67]
	v_mfma_f32_16x16x32_bf16 v[68:71], v[158:161], v[198:201], v[68:71]
	v_mfma_f32_16x16x32_bf16 v[68:71], v[162:165], v[202:205], v[68:71]
	s_setprio 2
	s_barrier
	v_mfma_f32_16x16x32_bf16 v[96:99], v[146:149], v[198:201], v[96:99]
	v_mfma_f32_16x16x32_bf16 v[96:99], v[154:157], v[202:205], v[96:99]
	v_mfma_f32_16x16x32_bf16 v[100:103], v[128:131], v[198:201], v[100:103]
	v_mfma_f32_16x16x32_bf16 v[100:103], v[142:145], v[202:205], v[100:103]
	s_setprio 0
	s_add_i32 s50, s72, s14
	s_mov_b32 m0, s50
	ds_read_b128 v[174:177], v153 offset:16384
	ds_read_b128 v[178:181], v153 offset:17408
	ds_read_b128 v[182:185], v153 offset:18432
	ds_read_b128 v[186:189], v153 offset:19456
	ds_read_b128 v[190:193], v153 offset:20480
	ds_read_b128 v[194:197], v153 offset:21504
	ds_read_b128 v[198:201], v153 offset:22528
	ds_read_b128 v[202:205], v153 offset:23552
	global_load_lds_dwordx4 v134, s[78:79]
	s_add_i32 m0, s50, 0x2000
	s_add_i32 s50, s73, s14
	s_add_u32 s98, s78, s6
	s_addc_u32 s99, s79, s7
	global_load_lds_dwordx4 v134, s[98:99]
	s_mov_b32 m0, s50
	s_nop 0
	s_add_u32 s98, s78, s8
	s_addc_u32 s99, s79, s9
	global_load_lds_dwordx4 v134, s[98:99]
	s_add_i32 m0, s50, 0x2000
	s_nop 0
	s_add_u32 s98, s78, s10
	s_addc_u32 s99, s79, s11
	global_load_lds_dwordx4 v134, s[98:99]
	s_mov_b32 m0, s20
	s_nop 0
	global_load_lds_dwordx4 v132, s[76:77]
	s_mov_b32 m0, s21
	s_nop 0
	s_add_u32 s98, s76, s6
	s_addc_u32 s99, s77, s7
	global_load_lds_dwordx4 v132, s[98:99]
	s_waitcnt vmcnt(8)
	s_waitcnt lgkmcnt(0)
	s_barrier
	s_setprio 1
	s_waitcnt lgkmcnt(0)
	v_mfma_f32_16x16x32_bf16 v[60:63], v[128:131], v[174:177], v[60:63]
	v_mfma_f32_16x16x32_bf16 v[60:63], v[142:145], v[178:181], v[60:63]
	v_mfma_f32_16x16x32_bf16 v[56:59], v[146:149], v[174:177], v[56:59]
	v_mfma_f32_16x16x32_bf16 v[56:59], v[154:157], v[178:181], v[56:59]
	v_mfma_f32_16x16x32_bf16 v[28:31], v[158:161], v[174:177], v[28:31]
	v_mfma_f32_16x16x32_bf16 v[28:31], v[162:165], v[178:181], v[28:31]
	v_mfma_f32_16x16x32_bf16 v[24:27], v[166:169], v[174:177], v[24:27]
	v_mfma_f32_16x16x32_bf16 v[24:27], v[170:173], v[178:181], v[24:27]
	v_mfma_f32_16x16x32_bf16 v[16:19], v[166:169], v[182:185], v[16:19]
	v_mfma_f32_16x16x32_bf16 v[16:19], v[170:173], v[186:189], v[16:19]
	v_mfma_f32_16x16x32_bf16 v[20:23], v[158:161], v[182:185], v[20:23]
	v_mfma_f32_16x16x32_bf16 v[20:23], v[162:165], v[186:189], v[20:23]
	v_mfma_f32_16x16x32_bf16 v[48:51], v[146:149], v[182:185], v[48:51]
	v_mfma_f32_16x16x32_bf16 v[48:51], v[154:157], v[186:189], v[48:51]
	v_mfma_f32_16x16x32_bf16 v[52:55], v[128:131], v[182:185], v[52:55]
	v_mfma_f32_16x16x32_bf16 v[52:55], v[142:145], v[186:189], v[52:55]
	s_setprio 0
	s_setprio 1
	v_mfma_f32_16x16x32_bf16 v[44:47], v[128:131], v[190:193], v[44:47]
	v_mfma_f32_16x16x32_bf16 v[44:47], v[142:145], v[194:197], v[44:47]
	v_mfma_f32_16x16x32_bf16 v[40:43], v[146:149], v[190:193], v[40:43]
	v_mfma_f32_16x16x32_bf16 v[40:43], v[154:157], v[194:197], v[40:43]
	v_mfma_f32_16x16x32_bf16 v[12:15], v[158:161], v[190:193], v[12:15]
	v_mfma_f32_16x16x32_bf16 v[12:15], v[162:165], v[194:197], v[12:15]
	v_mfma_f32_16x16x32_bf16 v[8:11], v[166:169], v[190:193], v[8:11]
	v_mfma_f32_16x16x32_bf16 v[8:11], v[170:173], v[194:197], v[8:11]
	v_mfma_f32_16x16x32_bf16 v[0:3], v[166:169], v[198:201], v[0:3]
	v_mfma_f32_16x16x32_bf16 v[0:3], v[170:173], v[202:205], v[0:3]
	v_mfma_f32_16x16x32_bf16 v[4:7], v[158:161], v[198:201], v[4:7]
	v_mfma_f32_16x16x32_bf16 v[4:7], v[162:165], v[202:205], v[4:7]
	s_setprio 2
	s_barrier
	v_mfma_f32_16x16x32_bf16 v[32:35], v[146:149], v[198:201], v[32:35]
	v_mfma_f32_16x16x32_bf16 v[32:35], v[154:157], v[202:205], v[32:35]
	v_mfma_f32_16x16x32_bf16 v[36:39], v[128:131], v[198:201], v[36:39]
	v_mfma_f32_16x16x32_bf16 v[36:39], v[142:145], v[202:205], v[36:39]
	s_setprio 0
	s_add_i32 s50, 0, 0x18000
	s_add_i32 s51, 0, 0x1c000
	v_add_u32_e32 v154, s50, v150
	v_add_u32_e32 v170, s51, v150
	ds_read_b128 v[128:131], v154
	ds_read_b128 v[142:145], v154 offset:1024
	ds_read_b128 v[146:149], v154 offset:2048
	ds_read_b128 v[154:157], v154 offset:3072
	ds_read_b128 v[158:161], v170
	ds_read_b128 v[162:165], v170 offset:1024
	ds_read_b128 v[166:169], v170 offset:2048
	ds_read_b128 v[170:173], v170 offset:3072
	s_mov_b32 m0, s33
	ds_read_b128 v[174:177], v153 offset:32768
	ds_read_b128 v[178:181], v153 offset:33792
	ds_read_b128 v[182:185], v153 offset:34816
	ds_read_b128 v[186:189], v153 offset:35840
	ds_read_b128 v[190:193], v153 offset:36864
	ds_read_b128 v[194:197], v153 offset:37888
	ds_read_b128 v[198:201], v153 offset:38912
	ds_read_b128 v[202:205], v153 offset:39936
	s_add_u32 s98, s76, s8
	s_addc_u32 s99, s77, s9
	global_load_lds_dwordx4 v132, s[98:99]
	s_mov_b32 m0, s64
	s_nop 0
	s_add_u32 s98, s76, s10
	s_addc_u32 s99, s77, s11
	global_load_lds_dwordx4 v132, s[98:99]
	s_waitcnt vmcnt(8)
	s_waitcnt lgkmcnt(0)
	s_barrier
	s_setprio 1
	s_waitcnt lgkmcnt(0)
	v_mfma_f32_16x16x32_bf16 v[124:127], v[128:131], v[174:177], v[124:127]
	v_mfma_f32_16x16x32_bf16 v[124:127], v[142:145], v[178:181], v[124:127]
	v_mfma_f32_16x16x32_bf16 v[120:123], v[146:149], v[174:177], v[120:123]
	v_mfma_f32_16x16x32_bf16 v[120:123], v[154:157], v[178:181], v[120:123]
	v_mfma_f32_16x16x32_bf16 v[92:95], v[158:161], v[174:177], v[92:95]
	v_mfma_f32_16x16x32_bf16 v[92:95], v[162:165], v[178:181], v[92:95]
	v_mfma_f32_16x16x32_bf16 v[88:91], v[166:169], v[174:177], v[88:91]
	v_mfma_f32_16x16x32_bf16 v[88:91], v[170:173], v[178:181], v[88:91]
	v_mfma_f32_16x16x32_bf16 v[80:83], v[166:169], v[182:185], v[80:83]
	v_mfma_f32_16x16x32_bf16 v[80:83], v[170:173], v[186:189], v[80:83]
	v_mfma_f32_16x16x32_bf16 v[84:87], v[158:161], v[182:185], v[84:87]
	v_mfma_f32_16x16x32_bf16 v[84:87], v[162:165], v[186:189], v[84:87]
	v_mfma_f32_16x16x32_bf16 v[112:115], v[146:149], v[182:185], v[112:115]
	v_mfma_f32_16x16x32_bf16 v[112:115], v[154:157], v[186:189], v[112:115]
	v_mfma_f32_16x16x32_bf16 v[116:119], v[128:131], v[182:185], v[116:119]
	v_mfma_f32_16x16x32_bf16 v[116:119], v[142:145], v[186:189], v[116:119]
	s_setprio 0
	s_setprio 1
	v_mfma_f32_16x16x32_bf16 v[108:111], v[128:131], v[190:193], v[108:111]
	v_mfma_f32_16x16x32_bf16 v[108:111], v[142:145], v[194:197], v[108:111]
	v_mfma_f32_16x16x32_bf16 v[104:107], v[146:149], v[190:193], v[104:107]
	v_mfma_f32_16x16x32_bf16 v[104:107], v[154:157], v[194:197], v[104:107]
	v_mfma_f32_16x16x32_bf16 v[76:79], v[158:161], v[190:193], v[76:79]
	v_mfma_f32_16x16x32_bf16 v[76:79], v[162:165], v[194:197], v[76:79]
	v_mfma_f32_16x16x32_bf16 v[72:75], v[166:169], v[190:193], v[72:75]
	v_mfma_f32_16x16x32_bf16 v[72:75], v[170:173], v[194:197], v[72:75]
	v_mfma_f32_16x16x32_bf16 v[64:67], v[166:169], v[198:201], v[64:67]
	v_mfma_f32_16x16x32_bf16 v[64:67], v[170:173], v[202:205], v[64:67]
	v_mfma_f32_16x16x32_bf16 v[68:71], v[158:161], v[198:201], v[68:71]
	v_mfma_f32_16x16x32_bf16 v[68:71], v[162:165], v[202:205], v[68:71]
	s_setprio 2
	s_barrier
	v_mfma_f32_16x16x32_bf16 v[96:99], v[146:149], v[198:201], v[96:99]
	v_mfma_f32_16x16x32_bf16 v[96:99], v[154:157], v[202:205], v[96:99]
	v_mfma_f32_16x16x32_bf16 v[100:103], v[128:131], v[198:201], v[100:103]
	v_mfma_f32_16x16x32_bf16 v[100:103], v[142:145], v[202:205], v[100:103]
	s_setprio 0
	s_add_i32 s50, s50, s14
	s_mov_b32 m0, s50
	ds_read_b128 v[174:177], v153 offset:49152
	ds_read_b128 v[178:181], v153 offset:50176
	ds_read_b128 v[182:185], v153 offset:51200
	ds_read_b128 v[186:189], v153 offset:52224
	ds_read_b128 v[190:193], v153 offset:53248
	ds_read_b128 v[194:197], v153 offset:54272
	ds_read_b128 v[198:201], v153 offset:55296
	ds_read_b128 v[202:205], v153 offset:56320
	s_add_u32 s98, s78, s24
	s_addc_u32 s99, s79, s25
	global_load_lds_dwordx4 v134, s[98:99]
	s_add_i32 m0, s50, 0x2000
	s_add_i32 s50, s51, s14
	s_add_u32 s98, s78, s34
	s_addc_u32 s99, s79, s35
	global_load_lds_dwordx4 v134, s[98:99]
	s_mov_b32 m0, s50
	s_add_u32 s98, s78, s36
	s_addc_u32 s99, s79, s37
	global_load_lds_dwordx4 v134, s[98:99]
	s_add_i32 m0, s50, 0x2000
	s_nop 0
	s_add_u32 s98, s78, s38
	s_addc_u32 s99, s79, s39
	global_load_lds_dwordx4 v134, s[98:99]
	s_mov_b32 m0, s66
	s_nop 0
	s_add_u32 s98, s76, s24
	s_addc_u32 s99, s77, s25
	global_load_lds_dwordx4 v132, s[98:99]
	s_mov_b32 m0, s67
	s_nop 0
	s_add_u32 s98, s76, s34
	s_addc_u32 s99, s77, s35
	global_load_lds_dwordx4 v132, s[98:99]
	s_waitcnt vmcnt(8)
	s_waitcnt lgkmcnt(0)
	s_barrier
	s_setprio 1
	s_waitcnt lgkmcnt(0)
	v_mfma_f32_16x16x32_bf16 v[60:63], v[128:131], v[174:177], v[60:63]
	v_mfma_f32_16x16x32_bf16 v[60:63], v[142:145], v[178:181], v[60:63]
	v_mfma_f32_16x16x32_bf16 v[56:59], v[146:149], v[174:177], v[56:59]
	v_mfma_f32_16x16x32_bf16 v[56:59], v[154:157], v[178:181], v[56:59]
	v_mfma_f32_16x16x32_bf16 v[28:31], v[158:161], v[174:177], v[28:31]
	v_mfma_f32_16x16x32_bf16 v[28:31], v[162:165], v[178:181], v[28:31]
	v_mfma_f32_16x16x32_bf16 v[24:27], v[166:169], v[174:177], v[24:27]
	v_mfma_f32_16x16x32_bf16 v[24:27], v[170:173], v[178:181], v[24:27]
	v_mfma_f32_16x16x32_bf16 v[16:19], v[166:169], v[182:185], v[16:19]
	v_mfma_f32_16x16x32_bf16 v[16:19], v[170:173], v[186:189], v[16:19]
	v_mfma_f32_16x16x32_bf16 v[20:23], v[158:161], v[182:185], v[20:23]
	v_mfma_f32_16x16x32_bf16 v[20:23], v[162:165], v[186:189], v[20:23]
	v_mfma_f32_16x16x32_bf16 v[48:51], v[146:149], v[182:185], v[48:51]
	v_mfma_f32_16x16x32_bf16 v[48:51], v[154:157], v[186:189], v[48:51]
	v_mfma_f32_16x16x32_bf16 v[52:55], v[128:131], v[182:185], v[52:55]
	v_mfma_f32_16x16x32_bf16 v[52:55], v[142:145], v[186:189], v[52:55]
	s_setprio 0
	s_setprio 1
	v_mfma_f32_16x16x32_bf16 v[44:47], v[128:131], v[190:193], v[44:47]
	v_mfma_f32_16x16x32_bf16 v[44:47], v[142:145], v[194:197], v[44:47]
	v_mfma_f32_16x16x32_bf16 v[40:43], v[146:149], v[190:193], v[40:43]
	v_mfma_f32_16x16x32_bf16 v[40:43], v[154:157], v[194:197], v[40:43]
	v_mfma_f32_16x16x32_bf16 v[12:15], v[158:161], v[190:193], v[12:15]
	v_mfma_f32_16x16x32_bf16 v[12:15], v[162:165], v[194:197], v[12:15]
	v_mfma_f32_16x16x32_bf16 v[8:11], v[166:169], v[190:193], v[8:11]
	v_mfma_f32_16x16x32_bf16 v[8:11], v[170:173], v[194:197], v[8:11]
	v_mfma_f32_16x16x32_bf16 v[0:3], v[166:169], v[198:201], v[0:3]
	v_mfma_f32_16x16x32_bf16 v[0:3], v[170:173], v[202:205], v[0:3]
	v_mfma_f32_16x16x32_bf16 v[4:7], v[158:161], v[198:201], v[4:7]
	v_mfma_f32_16x16x32_bf16 v[4:7], v[162:165], v[202:205], v[4:7]
	s_setprio 2
	s_barrier
	v_mfma_f32_16x16x32_bf16 v[32:35], v[146:149], v[198:201], v[32:35]
	v_mfma_f32_16x16x32_bf16 v[32:35], v[154:157], v[202:205], v[32:35]
	v_mfma_f32_16x16x32_bf16 v[36:39], v[128:131], v[198:201], v[36:39]
	v_mfma_f32_16x16x32_bf16 v[36:39], v[142:145], v[202:205], v[36:39]
	s_setprio 0
	s_add_i32 s62, s62, 2
	s_add_u32 s74, s74, 0x100
	s_addc_u32 s75, s75, 0
	s_add_u32 s60, s60, 0x100
	s_addc_u32 s61, s61, 0
	s_cmp_gt_u32 s62, 61
	s_cbranch_scc0 .LBB0_627
	s_and_b64 vcc, exec, s[40:41]
	s_cbranch_vccz .LBB0_630
	s_barrier

.Lcm4_skip:
.LBB0_800:
	ds_read_b128 v[128:131], v187
	ds_read_b128 v[132:135], v187 offset:1024
	ds_read_b128 v[136:139], v187 offset:2048
	ds_read_b128 v[140:143], v187 offset:3072
	ds_read_b128 v[144:147], v188
	ds_read_b128 v[148:151], v188 offset:1024
	ds_read_b128 v[152:155], v188 offset:2048
	ds_read_b128 v[156:159], v188 offset:3072
	s_add_u32 s9, s6, 0xfff80080
	s_addc_u32 s50, s7, -1
	s_cmp_eq_u32 s8, 28
	s_cselect_b32 vcc_hi, s5, s50
	s_cselect_b32 vcc_lo, s10, s9
	s_cselect_b32 s51, s11, s78
	s_cselect_b32 s50, s73, s75
	s_add_i32 m0, s65, 0xc000
	ds_read_b128 v[160:163], v189
	ds_read_b128 v[164:167], v189 offset:1024
	ds_read_b128 v[168:171], v189 offset:2048
	ds_read_b128 v[192:195], v189 offset:3072
	ds_read_b128 v[196:199], v189 offset:4096
	ds_read_b128 v[200:203], v189 offset:5120
	ds_read_b128 v[204:207], v189 offset:6144
	ds_read_b128 v[208:211], v189 offset:7168
	global_load_lds_dwordx4 v178, s[6:7]
	s_add_i32 m0, s65, 0xe000
	s_nop 0
	s_add_u32 s98, s6, s36
	s_addc_u32 s99, s7, s37
	global_load_lds_dwordx4 v178, s[98:99]
	s_waitcnt vmcnt(8)
	s_waitcnt lgkmcnt(0)
	s_barrier
	s_setprio 1
	s_waitcnt lgkmcnt(0)
	v_mfma_i32_16x16x64_i8 v[84:87], v[128:131], v[160:163], v[84:87]
	v_mfma_i32_16x16x64_i8 v[84:87], v[132:135], v[164:167], v[84:87]
	v_mfma_i32_16x16x64_i8 v[16:19], v[136:139], v[160:163], v[16:19]
	v_mfma_i32_16x16x64_i8 v[16:19], v[140:143], v[164:167], v[16:19]
	v_mfma_i32_16x16x64_i8 v[124:127], v[144:147], v[160:163], v[124:127]
	v_mfma_i32_16x16x64_i8 v[124:127], v[148:151], v[164:167], v[124:127]
	v_mfma_i32_16x16x64_i8 v[68:71], v[152:155], v[160:163], v[68:71]
	v_mfma_i32_16x16x64_i8 v[68:71], v[156:159], v[164:167], v[68:71]
	v_mfma_i32_16x16x64_i8 v[72:75], v[152:155], v[168:171], v[72:75]
	v_mfma_i32_16x16x64_i8 v[72:75], v[156:159], v[192:195], v[72:75]
	v_mfma_i32_16x16x64_i8 v[120:123], v[144:147], v[168:171], v[120:123]
	v_mfma_i32_16x16x64_i8 v[120:123], v[148:151], v[192:195], v[120:123]
	v_mfma_i32_16x16x64_i8 v[20:23], v[136:139], v[168:171], v[20:23]
	v_mfma_i32_16x16x64_i8 v[20:23], v[140:143], v[192:195], v[20:23]
	v_mfma_i32_16x16x64_i8 v[88:91], v[128:131], v[168:171], v[88:91]
	v_mfma_i32_16x16x64_i8 v[88:91], v[132:135], v[192:195], v[88:91]
	s_setprio 0
	s_setprio 1
	v_mfma_i32_16x16x64_i8 v[92:95], v[128:131], v[196:199], v[92:95]
	v_mfma_i32_16x16x64_i8 v[92:95], v[132:135], v[200:203], v[92:95]
	v_mfma_i32_16x16x64_i8 v[24:27], v[136:139], v[196:199], v[24:27]
	v_mfma_i32_16x16x64_i8 v[24:27], v[140:143], v[200:203], v[24:27]
	v_mfma_i32_16x16x64_i8 v[116:119], v[144:147], v[196:199], v[116:119]
	v_mfma_i32_16x16x64_i8 v[116:119], v[148:151], v[200:203], v[116:119]
	v_mfma_i32_16x16x64_i8 v[80:83], v[152:155], v[196:199], v[80:83]
	v_mfma_i32_16x16x64_i8 v[80:83], v[156:159], v[200:203], v[80:83]
	v_mfma_i32_16x16x64_i8 v[60:63], v[152:155], v[204:207], v[60:63]
	v_mfma_i32_16x16x64_i8 v[60:63], v[156:159], v[208:211], v[60:63]
	v_mfma_i32_16x16x64_i8 v[112:115], v[144:147], v[204:207], v[112:115]
	v_mfma_i32_16x16x64_i8 v[112:115], v[148:151], v[208:211], v[112:115]
	s_setprio 2
	s_barrier
	v_mfma_i32_16x16x64_i8 v[28:31], v[136:139], v[204:207], v[28:31]
	v_mfma_i32_16x16x64_i8 v[28:31], v[140:143], v[208:211], v[28:31]
	v_mfma_i32_16x16x64_i8 v[96:99], v[128:131], v[204:207], v[96:99]
	v_mfma_i32_16x16x64_i8 v[96:99], v[132:135], v[208:211], v[96:99]
	s_setprio 0
	s_add_i32 s9, s80, s33
	s_mov_b64 s[100:101], s[50:51]
	s_mov_b32 m0, s9
	ds_read_b128 v[160:163], v189 offset:16384
	ds_read_b128 v[164:167], v189 offset:17408
	ds_read_b128 v[168:171], v189 offset:18432
	ds_read_b128 v[192:195], v189 offset:19456
	ds_read_b128 v[196:199], v189 offset:20480
	ds_read_b128 v[200:203], v189 offset:21504
	ds_read_b128 v[204:207], v189 offset:22528
	ds_read_b128 v[208:211], v189 offset:23552
	global_load_lds_dwordx4 v174, s[50:51]
	s_add_i32 m0, s9, 0x2000
	s_add_i32 s9, s81, s33
	s_add_u32 s98, s50, s36
	s_addc_u32 s99, s51, s37
	global_load_lds_dwordx4 v174, s[98:99]
	s_mov_b32 m0, s9
	s_nop 0
	s_add_u32 s98, s50, s38
	s_addc_u32 s99, s51, s39
	global_load_lds_dwordx4 v174, s[98:99]
	s_add_i32 m0, s9, 0x2000
	s_nop 0
	s_add_u32 s98, s50, s40
	s_addc_u32 s99, s51, s41
	global_load_lds_dwordx4 v174, s[98:99]
	s_mov_b32 m0, s65
	s_nop 0
	global_load_lds_dwordx4 v172, vcc
	s_mov_b32 m0, s67
	s_nop 0
	s_add_u32 s98, vcc_lo, s36
	s_addc_u32 s99, vcc_hi, s37
	global_load_lds_dwordx4 v172, s[98:99]
	s_waitcnt vmcnt(8)
	s_waitcnt lgkmcnt(0)
	s_barrier
	s_setprio 1
	s_waitcnt lgkmcnt(0)
	v_mfma_i32_16x16x64_i8 v[48:51], v[128:131], v[160:163], v[48:51]
	v_mfma_i32_16x16x64_i8 v[48:51], v[132:135], v[164:167], v[48:51]
	v_mfma_i32_16x16x64_i8 v[0:3], v[136:139], v[160:163], v[0:3]
	v_mfma_i32_16x16x64_i8 v[0:3], v[140:143], v[164:167], v[0:3]
	v_mfma_i32_16x16x64_i8 v[108:111], v[144:147], v[160:163], v[108:111]
	v_mfma_i32_16x16x64_i8 v[108:111], v[148:151], v[164:167], v[108:111]
	v_mfma_i32_16x16x64_i8 v[44:47], v[152:155], v[160:163], v[44:47]
	v_mfma_i32_16x16x64_i8 v[44:47], v[156:159], v[164:167], v[44:47]
	v_mfma_i32_16x16x64_i8 v[40:43], v[152:155], v[168:171], v[40:43]
	v_mfma_i32_16x16x64_i8 v[40:43], v[156:159], v[192:195], v[40:43]
	v_mfma_i32_16x16x64_i8 v[104:107], v[144:147], v[168:171], v[104:107]
	v_mfma_i32_16x16x64_i8 v[104:107], v[148:151], v[192:195], v[104:107]
	v_mfma_i32_16x16x64_i8 v[4:7], v[136:139], v[168:171], v[4:7]
	v_mfma_i32_16x16x64_i8 v[4:7], v[140:143], v[192:195], v[4:7]
	v_mfma_i32_16x16x64_i8 v[52:55], v[128:131], v[168:171], v[52:55]
	v_mfma_i32_16x16x64_i8 v[52:55], v[132:135], v[192:195], v[52:55]
	s_setprio 0
	s_setprio 1
	v_mfma_i32_16x16x64_i8 v[56:59], v[128:131], v[196:199], v[56:59]
	v_mfma_i32_16x16x64_i8 v[56:59], v[132:135], v[200:203], v[56:59]
	v_mfma_i32_16x16x64_i8 v[8:11], v[136:139], v[196:199], v[8:11]
	v_mfma_i32_16x16x64_i8 v[8:11], v[140:143], v[200:203], v[8:11]
	v_mfma_i32_16x16x64_i8 v[100:103], v[144:147], v[196:199], v[100:103]
	v_mfma_i32_16x16x64_i8 v[100:103], v[148:151], v[200:203], v[100:103]
	v_mfma_i32_16x16x64_i8 v[32:35], v[152:155], v[196:199], v[32:35]
	v_mfma_i32_16x16x64_i8 v[32:35], v[156:159], v[200:203], v[32:35]
	v_mfma_i32_16x16x64_i8 v[36:39], v[152:155], v[204:207], v[36:39]
	v_mfma_i32_16x16x64_i8 v[36:39], v[156:159], v[208:211], v[36:39]
	v_mfma_i32_16x16x64_i8 v[76:79], v[144:147], v[204:207], v[76:79]
	v_mfma_i32_16x16x64_i8 v[76:79], v[148:151], v[208:211], v[76:79]
	s_setprio 2
	s_barrier
	v_mfma_i32_16x16x64_i8 v[12:15], v[136:139], v[204:207], v[12:15]
	v_mfma_i32_16x16x64_i8 v[12:15], v[140:143], v[208:211], v[12:15]
	v_mfma_i32_16x16x64_i8 v[64:67], v[128:131], v[204:207], v[64:67]
	v_mfma_i32_16x16x64_i8 v[64:67], v[132:135], v[208:211], v[64:67]
	s_setprio 0
	s_add_i32 s9, 0, 0x18000
	s_add_i32 s50, 0, 0x1c000
	v_add_u32_e32 v140, s9, v186
	v_add_u32_e32 v156, s50, v186
	ds_read_b128 v[128:131], v140
	ds_read_b128 v[132:135], v140 offset:1024
	ds_read_b128 v[136:139], v140 offset:2048
	ds_read_b128 v[140:143], v140 offset:3072
	ds_read_b128 v[144:147], v156
	ds_read_b128 v[148:151], v156 offset:1024
	ds_read_b128 v[152:155], v156 offset:2048
	ds_read_b128 v[156:159], v156 offset:3072
	s_mov_b32 m0, s71
	ds_read_b128 v[160:163], v189 offset:32768
	ds_read_b128 v[164:167], v189 offset:33792
	ds_read_b128 v[168:171], v189 offset:34816
	ds_read_b128 v[192:195], v189 offset:35840
	ds_read_b128 v[196:199], v189 offset:36864
	ds_read_b128 v[200:203], v189 offset:37888
	ds_read_b128 v[204:207], v189 offset:38912
	ds_read_b128 v[208:211], v189 offset:39936
	s_add_u32 s98, vcc_lo, s38
	s_addc_u32 s99, vcc_hi, s39
	global_load_lds_dwordx4 v172, s[98:99]
	s_mov_b32 m0, s82
	s_nop 0
	s_add_u32 s98, vcc_lo, s40
	s_addc_u32 s99, vcc_hi, s41
	global_load_lds_dwordx4 v172, s[98:99]
	s_waitcnt vmcnt(8)
	s_waitcnt lgkmcnt(0)
	s_barrier
	s_setprio 1
	s_waitcnt lgkmcnt(0)
	v_mfma_i32_16x16x64_i8 v[84:87], v[128:131], v[160:163], v[84:87]
	v_mfma_i32_16x16x64_i8 v[84:87], v[132:135], v[164:167], v[84:87]
	v_mfma_i32_16x16x64_i8 v[16:19], v[136:139], v[160:163], v[16:19]
	v_mfma_i32_16x16x64_i8 v[16:19], v[140:143], v[164:167], v[16:19]
	v_mfma_i32_16x16x64_i8 v[124:127], v[144:147], v[160:163], v[124:127]
	v_mfma_i32_16x16x64_i8 v[124:127], v[148:151], v[164:167], v[124:127]
	v_mfma_i32_16x16x64_i8 v[68:71], v[152:155], v[160:163], v[68:71]
	v_mfma_i32_16x16x64_i8 v[68:71], v[156:159], v[164:167], v[68:71]
	v_mfma_i32_16x16x64_i8 v[72:75], v[152:155], v[168:171], v[72:75]
	v_mfma_i32_16x16x64_i8 v[72:75], v[156:159], v[192:195], v[72:75]
	v_mfma_i32_16x16x64_i8 v[120:123], v[144:147], v[168:171], v[120:123]
	v_mfma_i32_16x16x64_i8 v[120:123], v[148:151], v[192:195], v[120:123]
	v_mfma_i32_16x16x64_i8 v[20:23], v[136:139], v[168:171], v[20:23]
	v_mfma_i32_16x16x64_i8 v[20:23], v[140:143], v[192:195], v[20:23]
	v_mfma_i32_16x16x64_i8 v[88:91], v[128:131], v[168:171], v[88:91]
	v_mfma_i32_16x16x64_i8 v[88:91], v[132:135], v[192:195], v[88:91]
	s_setprio 0
	s_setprio 1
	v_mfma_i32_16x16x64_i8 v[92:95], v[128:131], v[196:199], v[92:95]
	v_mfma_i32_16x16x64_i8 v[92:95], v[132:135], v[200:203], v[92:95]
	v_mfma_i32_16x16x64_i8 v[24:27], v[136:139], v[196:199], v[24:27]
	v_mfma_i32_16x16x64_i8 v[24:27], v[140:143], v[200:203], v[24:27]
	v_mfma_i32_16x16x64_i8 v[116:119], v[144:147], v[196:199], v[116:119]
	v_mfma_i32_16x16x64_i8 v[116:119], v[148:151], v[200:203], v[116:119]
	v_mfma_i32_16x16x64_i8 v[80:83], v[152:155], v[196:199], v[80:83]
	v_mfma_i32_16x16x64_i8 v[80:83], v[156:159], v[200:203], v[80:83]
	v_mfma_i32_16x16x64_i8 v[60:63], v[152:155], v[204:207], v[60:63]
	v_mfma_i32_16x16x64_i8 v[60:63], v[156:159], v[208:211], v[60:63]
	v_mfma_i32_16x16x64_i8 v[112:115], v[144:147], v[204:207], v[112:115]
	v_mfma_i32_16x16x64_i8 v[112:115], v[148:151], v[208:211], v[112:115]
	s_setprio 2
	s_barrier
	v_mfma_i32_16x16x64_i8 v[28:31], v[136:139], v[204:207], v[28:31]
	v_mfma_i32_16x16x64_i8 v[28:31], v[140:143], v[208:211], v[28:31]
	v_mfma_i32_16x16x64_i8 v[96:99], v[128:131], v[204:207], v[96:99]
	v_mfma_i32_16x16x64_i8 v[96:99], v[132:135], v[208:211], v[96:99]
	s_setprio 0
	s_add_i32 s9, s9, s33
	s_mov_b32 m0, s9
	ds_read_b128 v[160:163], v189 offset:49152
	ds_read_b128 v[164:167], v189 offset:50176
	ds_read_b128 v[168:171], v189 offset:51200
	ds_read_b128 v[192:195], v189 offset:52224
	ds_read_b128 v[196:199], v189 offset:53248
	ds_read_b128 v[200:203], v189 offset:54272
	ds_read_b128 v[204:207], v189 offset:55296
	ds_read_b128 v[208:211], v189 offset:56320
	s_add_u32 s98, s100, s44
	s_addc_u32 s99, s101, s45
	global_load_lds_dwordx4 v174, s[98:99]
	s_add_i32 m0, s9, 0x2000
	s_add_i32 s9, s50, s33
	s_add_u32 s98, s100, s46
	s_addc_u32 s99, s101, s47
	global_load_lds_dwordx4 v174, s[98:99]
	s_mov_b32 m0, s9
	s_add_u32 s98, s100, s48
	s_addc_u32 s99, s101, s49
	global_load_lds_dwordx4 v174, s[98:99]
	s_add_i32 m0, s9, 0x2000
	s_nop 0
	s_add_u32 s98, s100, s52
	s_addc_u32 s99, s101, s53
	global_load_lds_dwordx4 v174, s[98:99]
	s_mov_b32 m0, s90
	s_nop 0
	s_add_u32 s98, vcc_lo, s44
	s_addc_u32 s99, vcc_hi, s45
	global_load_lds_dwordx4 v172, s[98:99]
	s_mov_b32 m0, s91
	s_nop 0
	s_add_u32 s98, vcc_lo, s46
	s_addc_u32 s99, vcc_hi, s47
	global_load_lds_dwordx4 v172, s[98:99]
	s_waitcnt vmcnt(8)
	s_waitcnt lgkmcnt(0)
	s_barrier
	s_setprio 1
	s_waitcnt lgkmcnt(0)
	v_mfma_i32_16x16x64_i8 v[48:51], v[128:131], v[160:163], v[48:51]
	v_mfma_i32_16x16x64_i8 v[48:51], v[132:135], v[164:167], v[48:51]
	v_mfma_i32_16x16x64_i8 v[0:3], v[136:139], v[160:163], v[0:3]
	v_mfma_i32_16x16x64_i8 v[0:3], v[140:143], v[164:167], v[0:3]
	v_mfma_i32_16x16x64_i8 v[108:111], v[144:147], v[160:163], v[108:111]
	v_mfma_i32_16x16x64_i8 v[108:111], v[148:151], v[164:167], v[108:111]
	v_mfma_i32_16x16x64_i8 v[44:47], v[152:155], v[160:163], v[44:47]
	v_mfma_i32_16x16x64_i8 v[44:47], v[156:159], v[164:167], v[44:47]
	v_mfma_i32_16x16x64_i8 v[40:43], v[152:155], v[168:171], v[40:43]
	v_mfma_i32_16x16x64_i8 v[40:43], v[156:159], v[192:195], v[40:43]
	v_mfma_i32_16x16x64_i8 v[104:107], v[144:147], v[168:171], v[104:107]
	v_mfma_i32_16x16x64_i8 v[104:107], v[148:151], v[192:195], v[104:107]
	v_mfma_i32_16x16x64_i8 v[4:7], v[136:139], v[168:171], v[4:7]
	v_mfma_i32_16x16x64_i8 v[4:7], v[140:143], v[192:195], v[4:7]
	v_mfma_i32_16x16x64_i8 v[52:55], v[128:131], v[168:171], v[52:55]
	v_mfma_i32_16x16x64_i8 v[52:55], v[132:135], v[192:195], v[52:55]
	s_setprio 0
	s_setprio 1
	v_mfma_i32_16x16x64_i8 v[56:59], v[128:131], v[196:199], v[56:59]
	v_mfma_i32_16x16x64_i8 v[56:59], v[132:135], v[200:203], v[56:59]
	v_mfma_i32_16x16x64_i8 v[8:11], v[136:139], v[196:199], v[8:11]
	v_mfma_i32_16x16x64_i8 v[8:11], v[140:143], v[200:203], v[8:11]
	v_mfma_i32_16x16x64_i8 v[100:103], v[144:147], v[196:199], v[100:103]
	v_mfma_i32_16x16x64_i8 v[100:103], v[148:151], v[200:203], v[100:103]
	v_mfma_i32_16x16x64_i8 v[32:35], v[152:155], v[196:199], v[32:35]
	v_mfma_i32_16x16x64_i8 v[32:35], v[156:159], v[200:203], v[32:35]
	v_mfma_i32_16x16x64_i8 v[36:39], v[152:155], v[204:207], v[36:39]
	v_mfma_i32_16x16x64_i8 v[36:39], v[156:159], v[208:211], v[36:39]
	v_mfma_i32_16x16x64_i8 v[76:79], v[144:147], v[204:207], v[76:79]
	v_mfma_i32_16x16x64_i8 v[76:79], v[148:151], v[208:211], v[76:79]
	s_setprio 2
	s_barrier
	v_mfma_i32_16x16x64_i8 v[12:15], v[136:139], v[204:207], v[12:15]
	v_mfma_i32_16x16x64_i8 v[12:15], v[140:143], v[208:211], v[12:15]
	v_mfma_i32_16x16x64_i8 v[64:67], v[128:131], v[204:207], v[64:67]
	v_mfma_i32_16x16x64_i8 v[64:67], v[132:135], v[208:211], v[64:67]
	s_setprio 0
	s_add_i32 s8, s8, 2
	s_add_u32 s75, s75, 0x100
	s_addc_u32 s78, s78, 0
	s_add_u32 s6, s6, 0x100
	s_addc_u32 s7, s7, 0
	s_cmp_gt_u32 s8, 29
	s_cbranch_scc0 .LBB0_800
	s_and_b64 vcc, exec, s[54:55]
	s_cbranch_vccz .LBB0_803
	s_barrier

.LBB0_1034:
	ds_read_b128 v[138:141], v151
	ds_read_b128 v[142:145], v151 offset:1024
	ds_read_b128 v[146:149], v151 offset:2048
	ds_read_b128 v[154:157], v151 offset:3072
	ds_read_b128 v[158:161], v152
	ds_read_b128 v[162:165], v152 offset:1024
	ds_read_b128 v[166:169], v152 offset:2048
	ds_read_b128 v[170:173], v152 offset:3072
	s_add_u32 s47, s44, 0xffd50080
	s_addc_u32 s64, s45, -1
	s_cmpk_eq_i32 s46, 0xa8
	s_cselect_b32 s65, s5, s64
	s_cselect_b32 s64, s4, s47
	s_cselect_b32 s67, s43, s63
	s_cselect_b32 s66, s42, s62
	s_add_i32 m0, s25, 0xc000
	ds_read_b128 v[174:177], v153
	ds_read_b128 v[178:181], v153 offset:1024
	ds_read_b128 v[182:185], v153 offset:2048
	ds_read_b128 v[186:189], v153 offset:3072
	ds_read_b128 v[190:193], v153 offset:4096
	ds_read_b128 v[194:197], v153 offset:5120
	ds_read_b128 v[198:201], v153 offset:6144
	ds_read_b128 v[202:205], v153 offset:7168
	global_load_lds_dwordx4 v132, s[44:45]
	s_add_i32 m0, s25, 0xe000
	s_nop 0
	s_add_u32 s98, s44, s0
	s_addc_u32 s99, s45, s1
	global_load_lds_dwordx4 v132, s[98:99]
	s_waitcnt vmcnt(8)
	s_waitcnt lgkmcnt(0)
	s_barrier
	s_setprio 1
	s_waitcnt lgkmcnt(0)
	v_mfma_f32_16x16x32_bf16 v[124:127], v[138:141], v[174:177], v[124:127]
	v_mfma_f32_16x16x32_bf16 v[124:127], v[142:145], v[178:181], v[124:127]
	v_mfma_f32_16x16x32_bf16 v[120:123], v[146:149], v[174:177], v[120:123]
	v_mfma_f32_16x16x32_bf16 v[120:123], v[154:157], v[178:181], v[120:123]
	v_mfma_f32_16x16x32_bf16 v[92:95], v[158:161], v[174:177], v[92:95]
	v_mfma_f32_16x16x32_bf16 v[92:95], v[162:165], v[178:181], v[92:95]
	v_mfma_f32_16x16x32_bf16 v[88:91], v[166:169], v[174:177], v[88:91]
	v_mfma_f32_16x16x32_bf16 v[88:91], v[170:173], v[178:181], v[88:91]
	v_mfma_f32_16x16x32_bf16 v[80:83], v[166:169], v[182:185], v[80:83]
	v_mfma_f32_16x16x32_bf16 v[80:83], v[170:173], v[186:189], v[80:83]
	v_mfma_f32_16x16x32_bf16 v[84:87], v[158:161], v[182:185], v[84:87]
	v_mfma_f32_16x16x32_bf16 v[84:87], v[162:165], v[186:189], v[84:87]
	v_mfma_f32_16x16x32_bf16 v[112:115], v[146:149], v[182:185], v[112:115]
	v_mfma_f32_16x16x32_bf16 v[112:115], v[154:157], v[186:189], v[112:115]
	v_mfma_f32_16x16x32_bf16 v[116:119], v[138:141], v[182:185], v[116:119]
	v_mfma_f32_16x16x32_bf16 v[116:119], v[142:145], v[186:189], v[116:119]
	s_setprio 0
	s_setprio 1
	v_mfma_f32_16x16x32_bf16 v[108:111], v[138:141], v[190:193], v[108:111]
	v_mfma_f32_16x16x32_bf16 v[108:111], v[142:145], v[194:197], v[108:111]
	v_mfma_f32_16x16x32_bf16 v[104:107], v[146:149], v[190:193], v[104:107]
	v_mfma_f32_16x16x32_bf16 v[104:107], v[154:157], v[194:197], v[104:107]
	v_mfma_f32_16x16x32_bf16 v[76:79], v[158:161], v[190:193], v[76:79]
	v_mfma_f32_16x16x32_bf16 v[76:79], v[162:165], v[194:197], v[76:79]
	v_mfma_f32_16x16x32_bf16 v[72:75], v[166:169], v[190:193], v[72:75]
	v_mfma_f32_16x16x32_bf16 v[72:75], v[170:173], v[194:197], v[72:75]
	v_mfma_f32_16x16x32_bf16 v[64:67], v[166:169], v[198:201], v[64:67]
	v_mfma_f32_16x16x32_bf16 v[64:67], v[170:173], v[202:205], v[64:67]
	v_mfma_f32_16x16x32_bf16 v[68:71], v[158:161], v[198:201], v[68:71]
	v_mfma_f32_16x16x32_bf16 v[68:71], v[162:165], v[202:205], v[68:71]
	s_setprio 2
	s_barrier
	v_mfma_f32_16x16x32_bf16 v[96:99], v[146:149], v[198:201], v[96:99]
	v_mfma_f32_16x16x32_bf16 v[96:99], v[154:157], v[202:205], v[96:99]
	v_mfma_f32_16x16x32_bf16 v[100:103], v[138:141], v[198:201], v[100:103]
	v_mfma_f32_16x16x32_bf16 v[100:103], v[142:145], v[202:205], v[100:103]
	s_setprio 0
	s_add_i32 s47, s56, s24
	s_mov_b32 m0, s47
	ds_read_b128 v[174:177], v153 offset:16384
	ds_read_b128 v[178:181], v153 offset:17408
	ds_read_b128 v[182:185], v153 offset:18432
	ds_read_b128 v[186:189], v153 offset:19456
	ds_read_b128 v[190:193], v153 offset:20480
	ds_read_b128 v[194:197], v153 offset:21504
	ds_read_b128 v[198:201], v153 offset:22528
	ds_read_b128 v[202:205], v153 offset:23552
	global_load_lds_dwordx4 v130, s[66:67]
	s_add_i32 m0, s47, 0x2000
	s_add_i32 s47, s57, s24
	s_add_u32 s98, s66, s0
	s_addc_u32 s99, s67, s1
	global_load_lds_dwordx4 v130, s[98:99]
	s_mov_b32 m0, s47
	s_nop 0
	s_add_u32 s98, s66, s6
	s_addc_u32 s99, s67, s7
	global_load_lds_dwordx4 v130, s[98:99]
	s_add_i32 m0, s47, 0x2000
	s_nop 0
	s_add_u32 s98, s66, s8
	s_addc_u32 s99, s67, s9
	global_load_lds_dwordx4 v130, s[98:99]
	s_mov_b64 s[100:101], s[64:65]
	s_mov_b32 m0, s25
	s_nop 0
	global_load_lds_dwordx4 v128, s[64:65]
	s_mov_b32 m0, s33
	s_nop 0
	s_add_u32 s98, s64, s0
	s_addc_u32 s99, s65, s1
	global_load_lds_dwordx4 v128, s[98:99]
	s_waitcnt vmcnt(8)
	s_waitcnt lgkmcnt(0)
	s_barrier
	s_setprio 1
	s_waitcnt lgkmcnt(0)
	v_mfma_f32_16x16x32_bf16 v[60:63], v[138:141], v[174:177], v[60:63]
	v_mfma_f32_16x16x32_bf16 v[60:63], v[142:145], v[178:181], v[60:63]
	v_mfma_f32_16x16x32_bf16 v[56:59], v[146:149], v[174:177], v[56:59]
	v_mfma_f32_16x16x32_bf16 v[56:59], v[154:157], v[178:181], v[56:59]
	v_mfma_f32_16x16x32_bf16 v[28:31], v[158:161], v[174:177], v[28:31]
	v_mfma_f32_16x16x32_bf16 v[28:31], v[162:165], v[178:181], v[28:31]
	v_mfma_f32_16x16x32_bf16 v[24:27], v[166:169], v[174:177], v[24:27]
	v_mfma_f32_16x16x32_bf16 v[24:27], v[170:173], v[178:181], v[24:27]
	v_mfma_f32_16x16x32_bf16 v[16:19], v[166:169], v[182:185], v[16:19]
	v_mfma_f32_16x16x32_bf16 v[16:19], v[170:173], v[186:189], v[16:19]
	v_mfma_f32_16x16x32_bf16 v[20:23], v[158:161], v[182:185], v[20:23]
	v_mfma_f32_16x16x32_bf16 v[20:23], v[162:165], v[186:189], v[20:23]
	v_mfma_f32_16x16x32_bf16 v[48:51], v[146:149], v[182:185], v[48:51]
	v_mfma_f32_16x16x32_bf16 v[48:51], v[154:157], v[186:189], v[48:51]
	v_mfma_f32_16x16x32_bf16 v[52:55], v[138:141], v[182:185], v[52:55]
	v_mfma_f32_16x16x32_bf16 v[52:55], v[142:145], v[186:189], v[52:55]
	s_setprio 0
	s_setprio 1
	v_mfma_f32_16x16x32_bf16 v[44:47], v[138:141], v[190:193], v[44:47]
	v_mfma_f32_16x16x32_bf16 v[44:47], v[142:145], v[194:197], v[44:47]
	v_mfma_f32_16x16x32_bf16 v[40:43], v[146:149], v[190:193], v[40:43]
	v_mfma_f32_16x16x32_bf16 v[40:43], v[154:157], v[194:197], v[40:43]
	v_mfma_f32_16x16x32_bf16 v[12:15], v[158:161], v[190:193], v[12:15]
	v_mfma_f32_16x16x32_bf16 v[12:15], v[162:165], v[194:197], v[12:15]
	v_mfma_f32_16x16x32_bf16 v[8:11], v[166:169], v[190:193], v[8:11]
	v_mfma_f32_16x16x32_bf16 v[8:11], v[170:173], v[194:197], v[8:11]
	v_mfma_f32_16x16x32_bf16 v[0:3], v[166:169], v[198:201], v[0:3]
	v_mfma_f32_16x16x32_bf16 v[0:3], v[170:173], v[202:205], v[0:3]
	v_mfma_f32_16x16x32_bf16 v[4:7], v[158:161], v[198:201], v[4:7]
	v_mfma_f32_16x16x32_bf16 v[4:7], v[162:165], v[202:205], v[4:7]
	s_setprio 2
	s_barrier
	v_mfma_f32_16x16x32_bf16 v[32:35], v[146:149], v[198:201], v[32:35]
	v_mfma_f32_16x16x32_bf16 v[32:35], v[154:157], v[202:205], v[32:35]
	v_mfma_f32_16x16x32_bf16 v[36:39], v[138:141], v[198:201], v[36:39]
	v_mfma_f32_16x16x32_bf16 v[36:39], v[142:145], v[202:205], v[36:39]
	s_setprio 0
	s_add_i32 s47, 0, 0x18000
	s_add_i32 s64, 0, 0x1c000
	v_add_u32_e32 v154, s47, v150
	v_add_u32_e32 v170, s64, v150
	ds_read_b128 v[138:141], v154
	ds_read_b128 v[142:145], v154 offset:1024
	ds_read_b128 v[146:149], v154 offset:2048
	ds_read_b128 v[154:157], v154 offset:3072
	ds_read_b128 v[158:161], v170
	ds_read_b128 v[162:165], v170 offset:1024
	ds_read_b128 v[166:169], v170 offset:2048
	ds_read_b128 v[170:173], v170 offset:3072
	s_mov_b32 m0, s48
	ds_read_b128 v[174:177], v153 offset:32768
	ds_read_b128 v[178:181], v153 offset:33792
	ds_read_b128 v[182:185], v153 offset:34816
	ds_read_b128 v[186:189], v153 offset:35840
	ds_read_b128 v[190:193], v153 offset:36864
	ds_read_b128 v[194:197], v153 offset:37888
	ds_read_b128 v[198:201], v153 offset:38912
	ds_read_b128 v[202:205], v153 offset:39936
	s_add_u32 s98, s100, s6
	s_addc_u32 s99, s101, s7
	global_load_lds_dwordx4 v128, s[98:99]
	s_mov_b32 m0, s49
	s_nop 0
	s_add_u32 s98, s100, s8
	s_addc_u32 s99, s101, s9
	global_load_lds_dwordx4 v128, s[98:99]
	s_waitcnt vmcnt(8)
	s_waitcnt lgkmcnt(0)
	s_barrier
	s_setprio 1
	s_waitcnt lgkmcnt(0)
	v_mfma_f32_16x16x32_bf16 v[124:127], v[138:141], v[174:177], v[124:127]
	v_mfma_f32_16x16x32_bf16 v[124:127], v[142:145], v[178:181], v[124:127]
	v_mfma_f32_16x16x32_bf16 v[120:123], v[146:149], v[174:177], v[120:123]
	v_mfma_f32_16x16x32_bf16 v[120:123], v[154:157], v[178:181], v[120:123]
	v_mfma_f32_16x16x32_bf16 v[92:95], v[158:161], v[174:177], v[92:95]
	v_mfma_f32_16x16x32_bf16 v[92:95], v[162:165], v[178:181], v[92:95]
	v_mfma_f32_16x16x32_bf16 v[88:91], v[166:169], v[174:177], v[88:91]
	v_mfma_f32_16x16x32_bf16 v[88:91], v[170:173], v[178:181], v[88:91]
	v_mfma_f32_16x16x32_bf16 v[80:83], v[166:169], v[182:185], v[80:83]
	v_mfma_f32_16x16x32_bf16 v[80:83], v[170:173], v[186:189], v[80:83]
	v_mfma_f32_16x16x32_bf16 v[84:87], v[158:161], v[182:185], v[84:87]
	v_mfma_f32_16x16x32_bf16 v[84:87], v[162:165], v[186:189], v[84:87]
	v_mfma_f32_16x16x32_bf16 v[112:115], v[146:149], v[182:185], v[112:115]
	v_mfma_f32_16x16x32_bf16 v[112:115], v[154:157], v[186:189], v[112:115]
	v_mfma_f32_16x16x32_bf16 v[116:119], v[138:141], v[182:185], v[116:119]
	v_mfma_f32_16x16x32_bf16 v[116:119], v[142:145], v[186:189], v[116:119]
	s_setprio 0
	s_setprio 1
	v_mfma_f32_16x16x32_bf16 v[108:111], v[138:141], v[190:193], v[108:111]
	v_mfma_f32_16x16x32_bf16 v[108:111], v[142:145], v[194:197], v[108:111]
	v_mfma_f32_16x16x32_bf16 v[104:107], v[146:149], v[190:193], v[104:107]
	v_mfma_f32_16x16x32_bf16 v[104:107], v[154:157], v[194:197], v[104:107]
	v_mfma_f32_16x16x32_bf16 v[76:79], v[158:161], v[190:193], v[76:79]
	v_mfma_f32_16x16x32_bf16 v[76:79], v[162:165], v[194:197], v[76:79]
	v_mfma_f32_16x16x32_bf16 v[72:75], v[166:169], v[190:193], v[72:75]
	v_mfma_f32_16x16x32_bf16 v[72:75], v[170:173], v[194:197], v[72:75]
	v_mfma_f32_16x16x32_bf16 v[64:67], v[166:169], v[198:201], v[64:67]
	v_mfma_f32_16x16x32_bf16 v[64:67], v[170:173], v[202:205], v[64:67]
	v_mfma_f32_16x16x32_bf16 v[68:71], v[158:161], v[198:201], v[68:71]
	v_mfma_f32_16x16x32_bf16 v[68:71], v[162:165], v[202:205], v[68:71]
	s_setprio 2
	s_barrier
	v_mfma_f32_16x16x32_bf16 v[96:99], v[146:149], v[198:201], v[96:99]
	v_mfma_f32_16x16x32_bf16 v[96:99], v[154:157], v[202:205], v[96:99]
	v_mfma_f32_16x16x32_bf16 v[100:103], v[138:141], v[198:201], v[100:103]
	v_mfma_f32_16x16x32_bf16 v[100:103], v[142:145], v[202:205], v[100:103]
	s_setprio 0
	s_add_i32 s47, s47, s24
	s_mov_b32 m0, s47
	ds_read_b128 v[174:177], v153 offset:49152
	ds_read_b128 v[178:181], v153 offset:50176
	ds_read_b128 v[182:185], v153 offset:51200
	ds_read_b128 v[186:189], v153 offset:52224
	ds_read_b128 v[190:193], v153 offset:53248
	ds_read_b128 v[194:197], v153 offset:54272
	ds_read_b128 v[198:201], v153 offset:55296
	ds_read_b128 v[202:205], v153 offset:56320
	s_add_u32 s98, s66, s16
	s_addc_u32 s99, s67, s17
	global_load_lds_dwordx4 v130, s[98:99]
	s_add_i32 m0, s47, 0x2000
	s_add_i32 s47, s64, s24
	s_add_u32 s98, s66, s20
	s_addc_u32 s99, s67, s21
	global_load_lds_dwordx4 v130, s[98:99]
	s_mov_b32 m0, s47
	s_add_u32 s98, s66, s34
	s_addc_u32 s99, s67, s35
	global_load_lds_dwordx4 v130, s[98:99]
	s_add_i32 m0, s47, 0x2000
	s_nop 0
	s_add_u32 s98, s66, s36
	s_addc_u32 s99, s67, s37
	global_load_lds_dwordx4 v130, s[98:99]
	s_mov_b32 m0, s51
	s_nop 0
	s_add_u32 s98, s100, s16
	s_addc_u32 s99, s101, s17
	global_load_lds_dwordx4 v128, s[98:99]
	s_mov_b32 m0, s52
	s_nop 0
	s_add_u32 s98, s100, s20
	s_addc_u32 s99, s101, s21
	global_load_lds_dwordx4 v128, s[98:99]
	s_waitcnt vmcnt(8)
	s_waitcnt lgkmcnt(0)
	s_barrier
	s_setprio 1
	s_waitcnt lgkmcnt(0)
	v_mfma_f32_16x16x32_bf16 v[60:63], v[138:141], v[174:177], v[60:63]
	v_mfma_f32_16x16x32_bf16 v[60:63], v[142:145], v[178:181], v[60:63]
	v_mfma_f32_16x16x32_bf16 v[56:59], v[146:149], v[174:177], v[56:59]
	v_mfma_f32_16x16x32_bf16 v[56:59], v[154:157], v[178:181], v[56:59]
	v_mfma_f32_16x16x32_bf16 v[28:31], v[158:161], v[174:177], v[28:31]
	v_mfma_f32_16x16x32_bf16 v[28:31], v[162:165], v[178:181], v[28:31]
	v_mfma_f32_16x16x32_bf16 v[24:27], v[166:169], v[174:177], v[24:27]
	v_mfma_f32_16x16x32_bf16 v[24:27], v[170:173], v[178:181], v[24:27]
	v_mfma_f32_16x16x32_bf16 v[16:19], v[166:169], v[182:185], v[16:19]
	v_mfma_f32_16x16x32_bf16 v[16:19], v[170:173], v[186:189], v[16:19]
	v_mfma_f32_16x16x32_bf16 v[20:23], v[158:161], v[182:185], v[20:23]
	v_mfma_f32_16x16x32_bf16 v[20:23], v[162:165], v[186:189], v[20:23]
	v_mfma_f32_16x16x32_bf16 v[48:51], v[146:149], v[182:185], v[48:51]
	v_mfma_f32_16x16x32_bf16 v[48:51], v[154:157], v[186:189], v[48:51]
	v_mfma_f32_16x16x32_bf16 v[52:55], v[138:141], v[182:185], v[52:55]
	v_mfma_f32_16x16x32_bf16 v[52:55], v[142:145], v[186:189], v[52:55]
	s_setprio 0
	s_setprio 1
	v_mfma_f32_16x16x32_bf16 v[44:47], v[138:141], v[190:193], v[44:47]
	v_mfma_f32_16x16x32_bf16 v[44:47], v[142:145], v[194:197], v[44:47]
	v_mfma_f32_16x16x32_bf16 v[40:43], v[146:149], v[190:193], v[40:43]
	v_mfma_f32_16x16x32_bf16 v[40:43], v[154:157], v[194:197], v[40:43]
	v_mfma_f32_16x16x32_bf16 v[12:15], v[158:161], v[190:193], v[12:15]
	v_mfma_f32_16x16x32_bf16 v[12:15], v[162:165], v[194:197], v[12:15]
	v_mfma_f32_16x16x32_bf16 v[8:11], v[166:169], v[190:193], v[8:11]
	v_mfma_f32_16x16x32_bf16 v[8:11], v[170:173], v[194:197], v[8:11]
	v_mfma_f32_16x16x32_bf16 v[0:3], v[166:169], v[198:201], v[0:3]
	v_mfma_f32_16x16x32_bf16 v[0:3], v[170:173], v[202:205], v[0:3]
	v_mfma_f32_16x16x32_bf16 v[4:7], v[158:161], v[198:201], v[4:7]
	v_mfma_f32_16x16x32_bf16 v[4:7], v[162:165], v[202:205], v[4:7]
	s_setprio 2
	s_barrier
	v_mfma_f32_16x16x32_bf16 v[32:35], v[146:149], v[198:201], v[32:35]
	v_mfma_f32_16x16x32_bf16 v[32:35], v[154:157], v[202:205], v[32:35]
	v_mfma_f32_16x16x32_bf16 v[36:39], v[138:141], v[198:201], v[36:39]
	v_mfma_f32_16x16x32_bf16 v[36:39], v[142:145], v[202:205], v[36:39]
	s_setprio 0
	s_add_i32 s46, s46, 2
	s_add_u32 s62, s62, 0x100
	s_addc_u32 s63, s63, 0
	s_add_u32 s44, s44, 0x100
	s_addc_u32 s45, s45, 0
	s_cmpk_gt_u32 s46, 0xa9
	s_cbranch_scc0 .LBB0_1034
	s_and_b64 vcc, exec, s[38:39]
	s_cbranch_vccz .LBB0_1037
	s_barrier

.LBB0_1180:
	ds_read_b128 v[112:115], v181
	ds_read_b128 v[116:119], v181 offset:1024
	ds_read_b128 v[128:131], v181 offset:2048
	ds_read_b128 v[142:145], v181 offset:3072
	ds_read_b128 v[146:149], v202
	ds_read_b128 v[150:153], v202 offset:1024
	ds_read_b128 v[154:157], v202 offset:2048
	ds_read_b128 v[168:171], v202 offset:3072
	s_add_u32 s49, s46, 0xfff80080
	s_addc_u32 s70, s47, -1
	s_cmp_eq_u32 s48, 28
	s_cselect_b32 s71, s39, s70
	s_cselect_b32 s70, s66, s49
	s_cselect_b32 s73, s37, s69
	s_cselect_b32 s72, s67, s68
	s_add_i32 m0, s45, 0xc000
	ds_read_b128 v[172:175], v203
	ds_read_b128 v[182:185], v203 offset:1024
	ds_read_b128 v[186:189], v203 offset:2048
	ds_read_b128 v[190:193], v203 offset:3072
	ds_read_b128 v[194:197], v203 offset:4096
	ds_read_b128 v[198:201], v203 offset:5120
	ds_read_b128 v[206:209], v203 offset:6144
	ds_read_b128 v[210:213], v203 offset:7168
	global_load_lds_dwordx4 v162, s[46:47]
	s_add_i32 m0, s45, 0xe000
	s_nop 0
	s_add_u32 s98, s46, s2
	s_addc_u32 s99, s47, s3
	global_load_lds_dwordx4 v162, s[98:99]
	s_waitcnt vmcnt(8)
	s_waitcnt lgkmcnt(0)
	s_barrier
	s_setprio 1
	s_waitcnt lgkmcnt(0)
	v_mfma_i32_16x16x64_i8 v[138:141], v[112:115], v[172:175], v[138:141]
	v_mfma_i32_16x16x64_i8 v[132:135], v[128:131], v[172:175], v[134:137]
	v_mfma_i32_16x16x64_i8 v[124:127], v[112:115], v[186:189], v[124:127]
	v_mfma_i32_16x16x64_i8 v[120:123], v[128:131], v[186:189], v[120:123]
	v_mfma_i32_16x16x64_i8 v[108:111], v[112:115], v[194:197], v[108:111]
	v_mfma_i32_16x16x64_i8 v[104:107], v[128:131], v[194:197], v[104:107]
	v_mfma_i32_16x16x64_i8 v[100:103], v[112:115], v[206:209], v[100:103]
	v_mfma_i32_16x16x64_i8 v[96:99], v[128:131], v[206:209], v[96:99]
	v_mfma_i32_16x16x64_i8 v[138:141], v[116:119], v[182:185], v[138:141]
	v_mfma_i32_16x16x64_i8 v[132:135], v[142:145], v[182:185], v[132:135]
	v_mfma_i32_16x16x64_i8 v[124:127], v[116:119], v[190:193], v[124:127]
	v_mfma_i32_16x16x64_i8 v[120:123], v[142:145], v[190:193], v[120:123]
	v_mfma_i32_16x16x64_i8 v[108:111], v[116:119], v[198:201], v[108:111]
	v_mfma_i32_16x16x64_i8 v[104:107], v[142:145], v[198:201], v[104:107]
	v_mfma_i32_16x16x64_i8 v[100:103], v[116:119], v[210:213], v[100:103]
	v_mfma_i32_16x16x64_i8 v[96:99], v[142:145], v[210:213], v[96:99]
	s_setprio 0
	s_setprio 1
	v_mfma_i32_16x16x64_i8 v[60:63], v[146:149], v[172:175], v[60:63]
	v_mfma_i32_16x16x64_i8 v[60:63], v[150:153], v[182:185], v[60:63]
	v_mfma_i32_16x16x64_i8 v[56:59], v[154:157], v[172:175], v[56:59]
	v_mfma_i32_16x16x64_i8 v[56:59], v[168:171], v[182:185], v[56:59]
	v_mfma_i32_16x16x64_i8 v[52:55], v[146:149], v[186:189], v[52:55]
	v_mfma_i32_16x16x64_i8 v[52:55], v[150:153], v[190:193], v[52:55]
	v_mfma_i32_16x16x64_i8 v[48:51], v[154:157], v[186:189], v[48:51]
	v_mfma_i32_16x16x64_i8 v[48:51], v[168:171], v[190:193], v[48:51]
	v_mfma_i32_16x16x64_i8 v[44:47], v[146:149], v[194:197], v[44:47]
	v_mfma_i32_16x16x64_i8 v[44:47], v[150:153], v[198:201], v[44:47]
	v_mfma_i32_16x16x64_i8 v[40:43], v[154:157], v[194:197], v[40:43]
	v_mfma_i32_16x16x64_i8 v[40:43], v[168:171], v[198:201], v[40:43]
	s_setprio 2
	s_barrier
	v_mfma_i32_16x16x64_i8 v[36:39], v[146:149], v[206:209], v[36:39]
	v_mfma_i32_16x16x64_i8 v[36:39], v[150:153], v[210:213], v[36:39]
	v_mfma_i32_16x16x64_i8 v[32:35], v[154:157], v[206:209], v[32:35]
	v_mfma_i32_16x16x64_i8 v[32:35], v[168:171], v[210:213], v[32:35]
	s_setprio 0
	s_add_i32 s49, s61, s33
	s_mov_b32 m0, s49
	ds_read_b128 v[172:175], v203 offset:16384
	ds_read_b128 v[182:185], v203 offset:17408
	ds_read_b128 v[186:189], v203 offset:18432
	ds_read_b128 v[190:193], v203 offset:19456
	ds_read_b128 v[194:197], v203 offset:20480
	ds_read_b128 v[198:201], v203 offset:21504
	ds_read_b128 v[206:209], v203 offset:22528
	ds_read_b128 v[210:213], v203 offset:23552
	global_load_lds_dwordx4 v160, s[72:73]
	s_add_i32 m0, s49, 0x2000
	s_add_i32 s49, s62, s33
	s_add_u32 s98, s72, s2
	s_addc_u32 s99, s73, s3
	global_load_lds_dwordx4 v160, s[98:99]
	s_mov_b32 m0, s49
	s_mov_b64 s[100:101], s[70:71]
	s_add_u32 s98, s72, s6
	s_addc_u32 s99, s73, s7
	global_load_lds_dwordx4 v160, s[98:99]
	s_add_i32 m0, s49, 0x2000
	s_nop 0
	s_add_u32 s98, s72, s8
	s_addc_u32 s99, s73, s9
	global_load_lds_dwordx4 v160, s[98:99]
	s_mov_b32 m0, s45
	s_nop 0
	global_load_lds_dwordx4 v158, s[70:71]
	s_mov_b32 m0, s50
	s_nop 0
	s_add_u32 s98, s70, s2
	s_addc_u32 s99, s71, s3
	global_load_lds_dwordx4 v158, s[98:99]
	s_waitcnt vmcnt(8)
	s_waitcnt lgkmcnt(0)
	s_barrier
	s_setprio 1
	s_waitcnt lgkmcnt(0)
	v_mfma_i32_16x16x64_i8 v[92:95], v[112:115], v[172:175], v[92:95]
	v_mfma_i32_16x16x64_i8 v[92:95], v[116:119], v[182:185], v[92:95]
	v_mfma_i32_16x16x64_i8 v[88:91], v[128:131], v[172:175], v[88:91]
	v_mfma_i32_16x16x64_i8 v[88:91], v[142:145], v[182:185], v[88:91]
	v_mfma_i32_16x16x64_i8 v[28:31], v[146:149], v[172:175], v[28:31]
	v_mfma_i32_16x16x64_i8 v[28:31], v[150:153], v[182:185], v[28:31]
	v_mfma_i32_16x16x64_i8 v[24:27], v[154:157], v[172:175], v[24:27]
	v_mfma_i32_16x16x64_i8 v[24:27], v[168:171], v[182:185], v[24:27]
	v_mfma_i32_16x16x64_i8 v[16:19], v[154:157], v[186:189], v[16:19]
	v_mfma_i32_16x16x64_i8 v[16:19], v[168:171], v[190:193], v[16:19]
	v_mfma_i32_16x16x64_i8 v[20:23], v[146:149], v[186:189], v[20:23]
	v_mfma_i32_16x16x64_i8 v[20:23], v[150:153], v[190:193], v[20:23]
	v_mfma_i32_16x16x64_i8 v[80:83], v[128:131], v[186:189], v[80:83]
	v_mfma_i32_16x16x64_i8 v[80:83], v[142:145], v[190:193], v[80:83]
	v_mfma_i32_16x16x64_i8 v[84:87], v[112:115], v[186:189], v[84:87]
	v_mfma_i32_16x16x64_i8 v[84:87], v[116:119], v[190:193], v[84:87]
	s_setprio 0
	s_setprio 1
	v_mfma_i32_16x16x64_i8 v[76:79], v[112:115], v[194:197], v[76:79]
	v_mfma_i32_16x16x64_i8 v[76:79], v[116:119], v[198:201], v[76:79]
	v_mfma_i32_16x16x64_i8 v[72:75], v[128:131], v[194:197], v[72:75]
	v_mfma_i32_16x16x64_i8 v[72:75], v[142:145], v[198:201], v[72:75]
	v_mfma_i32_16x16x64_i8 v[12:15], v[146:149], v[194:197], v[12:15]
	v_mfma_i32_16x16x64_i8 v[12:15], v[150:153], v[198:201], v[12:15]
	v_mfma_i32_16x16x64_i8 v[8:11], v[154:157], v[194:197], v[8:11]
	v_mfma_i32_16x16x64_i8 v[8:11], v[168:171], v[198:201], v[8:11]
	v_mfma_i32_16x16x64_i8 v[0:3], v[154:157], v[206:209], v[0:3]
	v_mfma_i32_16x16x64_i8 v[0:3], v[168:171], v[210:213], v[0:3]
	v_mfma_i32_16x16x64_i8 v[4:7], v[146:149], v[206:209], v[4:7]
	v_mfma_i32_16x16x64_i8 v[4:7], v[150:153], v[210:213], v[4:7]
	s_setprio 2
	s_barrier
	v_mfma_i32_16x16x64_i8 v[64:67], v[128:131], v[206:209], v[64:67]
	v_mfma_i32_16x16x64_i8 v[64:67], v[142:145], v[210:213], v[64:67]
	v_mfma_i32_16x16x64_i8 v[68:71], v[112:115], v[206:209], v[68:71]
	v_mfma_i32_16x16x64_i8 v[68:71], v[116:119], v[210:213], v[68:71]
	s_setprio 0
	s_add_i32 s49, 0, 0x18000
	v_add_u32_e32 v136, s49, v179
	s_add_i32 s70, 0, 0x1c000
	ds_read_b128 v[112:115], v136
	ds_read_b128 v[116:119], v136 offset:1024
	ds_read_b128 v[128:131], v136 offset:2048
	ds_read_b128 v[142:145], v136 offset:3072
	v_add_u32_e32 v136, s70, v179
	ds_read_b128 v[146:149], v136
	ds_read_b128 v[150:153], v136 offset:1024
	ds_read_b128 v[154:157], v136 offset:2048
	ds_read_b128 v[168:171], v136 offset:3072
	s_mov_b32 m0, s51
	ds_read_b128 v[172:175], v203 offset:32768
	ds_read_b128 v[182:185], v203 offset:33792
	ds_read_b128 v[186:189], v203 offset:34816
	ds_read_b128 v[190:193], v203 offset:35840
	ds_read_b128 v[194:197], v203 offset:36864
	ds_read_b128 v[198:201], v203 offset:37888
	ds_read_b128 v[206:209], v203 offset:38912
	ds_read_b128 v[210:213], v203 offset:39936
	s_add_u32 s98, s100, s6
	s_addc_u32 s99, s101, s7
	global_load_lds_dwordx4 v158, s[98:99]
	s_mov_b32 m0, s52
	s_nop 0
	s_add_u32 s98, s100, s8
	s_addc_u32 s99, s101, s9
	global_load_lds_dwordx4 v158, s[98:99]
	s_waitcnt vmcnt(8)
	s_waitcnt lgkmcnt(0)
	s_barrier
	s_setprio 1
	s_waitcnt lgkmcnt(0)
	v_mfma_i32_16x16x64_i8 v[136:139], v[112:115], v[172:175], v[138:141]
	v_mfma_i32_16x16x64_i8 v[132:135], v[128:131], v[172:175], v[132:135]
	v_mfma_i32_16x16x64_i8 v[124:127], v[112:115], v[186:189], v[124:127]
	v_mfma_i32_16x16x64_i8 v[120:123], v[128:131], v[186:189], v[120:123]
	v_mfma_i32_16x16x64_i8 v[108:111], v[112:115], v[194:197], v[108:111]
	v_mfma_i32_16x16x64_i8 v[104:107], v[128:131], v[194:197], v[104:107]
	v_mfma_i32_16x16x64_i8 v[100:103], v[112:115], v[206:209], v[100:103]
	v_mfma_i32_16x16x64_i8 v[96:99], v[128:131], v[206:209], v[96:99]
	v_mfma_i32_16x16x64_i8 v[138:141], v[116:119], v[182:185], v[136:139]
	v_mfma_i32_16x16x64_i8 v[134:137], v[142:145], v[182:185], v[132:135]
	v_mfma_i32_16x16x64_i8 v[124:127], v[116:119], v[190:193], v[124:127]
	v_mfma_i32_16x16x64_i8 v[120:123], v[142:145], v[190:193], v[120:123]
	v_mfma_i32_16x16x64_i8 v[108:111], v[116:119], v[198:201], v[108:111]
	v_mfma_i32_16x16x64_i8 v[104:107], v[142:145], v[198:201], v[104:107]
	v_mfma_i32_16x16x64_i8 v[100:103], v[116:119], v[210:213], v[100:103]
	v_mfma_i32_16x16x64_i8 v[96:99], v[142:145], v[210:213], v[96:99]
	s_setprio 0
	s_setprio 1
	v_mfma_i32_16x16x64_i8 v[60:63], v[146:149], v[172:175], v[60:63]
	v_mfma_i32_16x16x64_i8 v[60:63], v[150:153], v[182:185], v[60:63]
	v_mfma_i32_16x16x64_i8 v[56:59], v[154:157], v[172:175], v[56:59]
	v_mfma_i32_16x16x64_i8 v[56:59], v[168:171], v[182:185], v[56:59]
	v_mfma_i32_16x16x64_i8 v[52:55], v[146:149], v[186:189], v[52:55]
	v_mfma_i32_16x16x64_i8 v[52:55], v[150:153], v[190:193], v[52:55]
	v_mfma_i32_16x16x64_i8 v[48:51], v[154:157], v[186:189], v[48:51]
	v_mfma_i32_16x16x64_i8 v[48:51], v[168:171], v[190:193], v[48:51]
	v_mfma_i32_16x16x64_i8 v[44:47], v[146:149], v[194:197], v[44:47]
	v_mfma_i32_16x16x64_i8 v[44:47], v[150:153], v[198:201], v[44:47]
	v_mfma_i32_16x16x64_i8 v[40:43], v[154:157], v[194:197], v[40:43]
	v_mfma_i32_16x16x64_i8 v[40:43], v[168:171], v[198:201], v[40:43]
	s_setprio 2
	s_barrier
	v_mfma_i32_16x16x64_i8 v[36:39], v[146:149], v[206:209], v[36:39]
	v_mfma_i32_16x16x64_i8 v[36:39], v[150:153], v[210:213], v[36:39]
	v_mfma_i32_16x16x64_i8 v[32:35], v[154:157], v[206:209], v[32:35]
	v_mfma_i32_16x16x64_i8 v[32:35], v[168:171], v[210:213], v[32:35]
	s_setprio 0
	s_add_i32 s49, s49, s33
	s_mov_b32 m0, s49
	ds_read_b128 v[172:175], v203 offset:49152
	ds_read_b128 v[182:185], v203 offset:50176
	ds_read_b128 v[186:189], v203 offset:51200
	ds_read_b128 v[190:193], v203 offset:52224
	ds_read_b128 v[194:197], v203 offset:53248
	ds_read_b128 v[198:201], v203 offset:54272
	ds_read_b128 v[206:209], v203 offset:55296
	ds_read_b128 v[210:213], v203 offset:56320
	s_add_u32 s98, s72, s16
	s_addc_u32 s99, s73, s17
	global_load_lds_dwordx4 v160, s[98:99]
	s_add_i32 m0, s49, 0x2000
	s_add_i32 s49, s70, s33
	s_add_u32 s98, s72, s18
	s_addc_u32 s99, s73, s19
	global_load_lds_dwordx4 v160, s[98:99]
	s_mov_b32 m0, s49
	s_nop 0
	s_add_u32 s98, s72, s20
	s_addc_u32 s99, s73, s21
	global_load_lds_dwordx4 v160, s[98:99]
	s_add_i32 m0, s49, 0x2000
	s_nop 0
	s_add_u32 s98, s72, s30
	s_addc_u32 s99, s73, s31
	global_load_lds_dwordx4 v160, s[98:99]
	s_mov_b32 m0, s54
	s_nop 0
	s_add_u32 s98, s100, s16
	s_addc_u32 s99, s101, s17
	global_load_lds_dwordx4 v158, s[98:99]
	s_mov_b32 m0, s55
	s_nop 0
	s_add_u32 s98, s100, s18
	s_addc_u32 s99, s101, s19
	global_load_lds_dwordx4 v158, s[98:99]
	s_waitcnt vmcnt(8)
	s_waitcnt lgkmcnt(0)
	s_barrier
	s_setprio 1
	s_waitcnt lgkmcnt(0)
	v_mfma_i32_16x16x64_i8 v[92:95], v[112:115], v[172:175], v[92:95]
	v_mfma_i32_16x16x64_i8 v[92:95], v[116:119], v[182:185], v[92:95]
	v_mfma_i32_16x16x64_i8 v[88:91], v[128:131], v[172:175], v[88:91]
	v_mfma_i32_16x16x64_i8 v[88:91], v[142:145], v[182:185], v[88:91]
	v_mfma_i32_16x16x64_i8 v[28:31], v[146:149], v[172:175], v[28:31]
	v_mfma_i32_16x16x64_i8 v[28:31], v[150:153], v[182:185], v[28:31]
	v_mfma_i32_16x16x64_i8 v[24:27], v[154:157], v[172:175], v[24:27]
	v_mfma_i32_16x16x64_i8 v[24:27], v[168:171], v[182:185], v[24:27]
	v_mfma_i32_16x16x64_i8 v[16:19], v[154:157], v[186:189], v[16:19]
	v_mfma_i32_16x16x64_i8 v[16:19], v[168:171], v[190:193], v[16:19]
	v_mfma_i32_16x16x64_i8 v[20:23], v[146:149], v[186:189], v[20:23]
	v_mfma_i32_16x16x64_i8 v[20:23], v[150:153], v[190:193], v[20:23]
	v_mfma_i32_16x16x64_i8 v[80:83], v[128:131], v[186:189], v[80:83]
	v_mfma_i32_16x16x64_i8 v[80:83], v[142:145], v[190:193], v[80:83]
	v_mfma_i32_16x16x64_i8 v[84:87], v[112:115], v[186:189], v[84:87]
	v_mfma_i32_16x16x64_i8 v[84:87], v[116:119], v[190:193], v[84:87]
	s_setprio 0
	s_setprio 1
	v_mfma_i32_16x16x64_i8 v[76:79], v[112:115], v[194:197], v[76:79]
	v_mfma_i32_16x16x64_i8 v[76:79], v[116:119], v[198:201], v[76:79]
	v_mfma_i32_16x16x64_i8 v[72:75], v[128:131], v[194:197], v[72:75]
	v_mfma_i32_16x16x64_i8 v[72:75], v[142:145], v[198:201], v[72:75]
	v_mfma_i32_16x16x64_i8 v[12:15], v[146:149], v[194:197], v[12:15]
	v_mfma_i32_16x16x64_i8 v[12:15], v[150:153], v[198:201], v[12:15]
	v_mfma_i32_16x16x64_i8 v[8:11], v[154:157], v[194:197], v[8:11]
	v_mfma_i32_16x16x64_i8 v[8:11], v[168:171], v[198:201], v[8:11]
	v_mfma_i32_16x16x64_i8 v[0:3], v[154:157], v[206:209], v[0:3]
	v_mfma_i32_16x16x64_i8 v[0:3], v[168:171], v[210:213], v[0:3]
	v_mfma_i32_16x16x64_i8 v[4:7], v[146:149], v[206:209], v[4:7]
	v_mfma_i32_16x16x64_i8 v[4:7], v[150:153], v[210:213], v[4:7]
	s_setprio 2
	s_barrier
	v_mfma_i32_16x16x64_i8 v[64:67], v[128:131], v[206:209], v[64:67]
	v_mfma_i32_16x16x64_i8 v[64:67], v[142:145], v[210:213], v[64:67]
	v_mfma_i32_16x16x64_i8 v[68:71], v[112:115], v[206:209], v[68:71]
	v_mfma_i32_16x16x64_i8 v[68:71], v[116:119], v[210:213], v[68:71]
	s_setprio 0
	s_add_i32 s48, s48, 2
	s_add_u32 s68, s68, 0x100
	s_addc_u32 s69, s69, 0
	s_add_u32 s46, s46, 0x100
	s_addc_u32 s47, s47, 0
	s_cmp_gt_u32 s48, 29
	s_cbranch_scc0 .LBB0_1180
	s_and_b64 vcc, exec, s[34:35]
	s_cbranch_vccz .LBB0_1183
	s_barrier
